# attn-C: p1 scale-fma into PV gaps (rare rescale path re-homed to v80-95), 24 exps moved from QK segment into PV gaps to balance VALU per segment
# speedup vs baseline: 1.0152x; 1.0062x over previous
; __device__ __forceinline__ int tid_() { int t = (int)threadIdx.x; asm volatile("" : "+v"(t)); return t; }
; __device__ __forceinline__ int v_st(int k, int c) { const int kk = (k & ~0xC) | ((k & 4) << 1) | ((k & 8) >> 1); return ((kk >> 3) * 4 + (c >> 5)) * 512 + ((kk & 7) * 32 + (c & 31)) * 2; }
; __device__ __forceinline__ int v_rd_base(int lane) { return ((lane & 3) << 3) | (((lane >> 2) & 3) << 6) | (((lane >> 4) & 1) << 5) | (((lane >> 5) & 1) << 8); }
; #define SLOAD(i, k0) do { sv0[i] = *(const bf16x8*)(&Vh[(long)((k0) + sr) * LDK + sc]); sv1[i] = *(const bf16x8*)(&Vh[(long)((k0) + 32 + sr) * LDK + sc]); \
;     sk0[i] = *(const bf16x8*)(&Kh[(long)((k0) + sr) * LDK + sc]); sk1[i] = *(const bf16x8*)(&Kh[(long)((k0) + 32 + sr) * LDK + sc]); } while (0)
; __device__ __forceinline__ void attn_dense_body(const bf16_t* __restrict__ Qb, const bf16_t* __restrict__ Kh, const bf16_t* __restrict__ Vh,
;                                                 bf16_t* __restrict__ Ob, int seq, char* lds, int dry) {
;     const int tid = tid_(), wid = tid >> 6, lane = tid & 63, r32 = lane & 31, hi = lane >> 5;
;     bf16_t* V_lds = (bf16_t*)lds; bf16_t* K_lds = (bf16_t*)(lds + 3 * SHM_V);
;     float* ws = (float*)(lds + 3 * SHM_V + 3 * SHM_K) + wid * 64; float* li_l = ws; float* al_l = ws + 32;
;     float m_reg = -1e30f, l_reg = 0; f32x16 o[4] = {}; bf16x8 qr[8];
;     const bf16_t* Qw = Qb + (long)(wid * QBLK + r32) * LDQ + hi * 8;
; #pragma unroll
;     for (int d0 = 0; d0 < 8; ++d0) qr[d0] = *reinterpret_cast<const bf16x8*>(Qw + d0 * 16);
;     const int sr = tid >> 4, sc = (tid & 15) * 8, vst0 = v_st(sr, sc), vst1 = v_st(32 + sr, sc);
;     const int vb0 = (int)(uintptr_t)V_lds + v_rd_base(lane);
;     bf16x8 sv0[2], sv1[2], sk0[2], sk1[2];
;     ...
;     f32x16 pA0, pA1, pB0, pB1; float mnA, mnB, alA, alB; bf16x8 pa0, pa1, pa2, pa3; const int NT = seq / KVBLK;
;     SLOAD(0, 0); asm volatile("s_waitcnt vmcnt(0)" ::: "memory"); SWRITE(0, 0); __syncthreads();
;     qkt(pA0, pA1, K_lds, qr, r32, hi); partialSM(pA0, pA1, m_reg, mnA, alA);
.LBB0_268:
	s_lshl_b32 s4, s29, 5
	s_cmpk_lt_i32 s29, 0x400
	s_movk_i32 s7, 0xc000
	s_cselect_b32 s5, 6, 4
	s_cselect_b32 s6, 63, 15
	s_cselect_b32 s7, s7, 0x7ffff000
	s_movk_i32 s37, 0x4000
	s_cselect_b32 s8, s37, 0xffff8000
	s_cselect_b32 s36, 0x100, 64
	s_lshr_b32 s12, s29, s5
	s_and_b32 s5, s6, s29
	s_and_b32 s4, s7, s4
	s_add_i32 s8, s4, s8
	s_lshl_b32 s4, s5, 8
	s_add_i32 s4, s8, s4
	s_and_b32 s6, s12, 7
	s_ashr_i32 s5, s4, 31
	s_mul_i32 s9, s4, 0xc00
	s_mul_hi_i32 s7, s4, 0xc00
	s_add_u32 s9, s30, s9
	s_addc_u32 s7, s31, s7
	s_lshl_b32 s35, s6, 7
	s_lshl_b32 s6, s6, 8
	s_add_u32 s10, s9, s6
	s_addc_u32 s11, s7, 0
	s_ashr_i32 s9, s8, 31
	s_mul_i32 s7, s8, 0xc00
	s_mul_hi_i32 s6, s8, 0xc00
	s_add_u32 s7, s30, s7
	s_addc_u32 s13, s31, s6
	s_lshl_b32 s6, s12, 6
	s_and_b32 s39, s6, 0x100
	v_mov_b32_e32 v70, v182
	s_add_u32 s6, s7, s39
	s_addc_u32 s7, s13, 0
	v_ashrrev_i32_e32 v48, 4, v70
	v_lshlrev_b32_e32 v18, 3, v70
	v_and_b32_e32 v71, 0x78, v18
	s_waitcnt vmcnt(0)
	v_mad_i64_i32 v[0:1], s[12:13], v48, s71, 0
	v_add_u32_e32 v19, 32, v48
	v_or_b32_e32 v0, v0, v71
	v_lshl_add_u64 v[8:9], v[0:1], 1, s[6:7]
	v_mad_i64_i32 v[4:5], s[12:13], v19, s71, 0
	global_load_dwordx4 v[0:3], v[8:9], off offset:2560
	v_or_b32_e32 v4, v4, v71
	v_lshl_add_u64 v[12:13], v[4:5], 1, s[6:7]
	global_load_dwordx4 v[4:7], v[12:13], off offset:2560
	s_nop 0
	global_load_dwordx4 v[8:11], v[8:9], off offset:2048
	s_nop 0
	global_load_dwordx4 v[12:15], v[12:13], off offset:2048
	v_ashrrev_i32_e32 v49, 1, v70
	s_movk_i32 s12, 0xffe0
	v_bfe_u32 v207, v70, 5, 1
	v_bfi_b32 v20, s12, v49, v70
	v_mov_b64_e32 v[16:17], s[10:11]
	v_mad_i64_i32 v[16:17], s[10:11], v20, s70, v[16:17]
	v_lshlrev_b32_e32 v96, 4, v207
	v_lshl_add_u64 v[16:17], v[16:17], 0, v[96:97]
	global_load_dwordx4 v[126:129], v[16:17], off
	global_load_dwordx4 v[122:125], v[16:17], off offset:32
	global_load_dwordx4 v[118:121], v[16:17], off offset:64
	global_load_dwordx4 v[114:117], v[16:17], off offset:96
	global_load_dwordx4 v[110:113], v[16:17], off offset:128
	global_load_dwordx4 v[106:109], v[16:17], off offset:160
	global_load_dwordx4 v[102:105], v[16:17], off offset:192
	global_load_dwordx4 v[98:101], v[16:17], off offset:224
	v_and_b32_e32 v21, 0xfffff0, v48
	v_lshlrev_b32_e32 v22, 1, v48
	v_lshrrev_b32_e32 v23, 1, v48
	v_and_b32_e32 v24, 3, v48
	v_and_or_b32 v21, v22, 8, v21
	v_and_or_b32 v22, v23, 4, v24
	v_and_b32_e32 v24, 0xfffff0, v19
	v_lshlrev_b32_e32 v26, 1, v19
	v_bfe_u32 v18, v18, 5, 2
	v_lshrrev_b32_e32 v21, 1, v21
	v_and_or_b32 v24, v26, 8, v24
	v_lshlrev_b32_e32 v23, 1, v71
	v_or_b32_e32 v21, v21, v18
	v_lshrrev_b32_e32 v24, 1, v24
	v_lshlrev_b32_e32 v22, 6, v22
	v_and_b32_e32 v27, 48, v23
	v_lshlrev_b32_e32 v21, 9, v21
	v_or_b32_e32 v18, v24, v18
	v_and_b32_e32 v20, 0x70, v70
	v_lshlrev_b32_e32 v25, 8, v48
	v_or3_b32 v216, v21, v22, v27
	v_lshlrev_b32_e32 v18, 9, v18
	v_bitop3_b32 v214, v23, v25, v20 bitop3:0xde
	v_and_b32_e32 v252, 0x80, v182
	v_lshlrev_b32_e32 v253, 4, v182
	v_and_b32_e32 v253, 0x80, v253
	v_xor_b32_e32 v214, v214, v252
	v_or3_b32 v217, v18, v22, v27
	v_add_u32_e32 v72, 0, v216
	v_and_b32_e32 v208, 31, v70
	v_lshlrev_b32_e32 v50, 4, v70
	v_add_u32_e32 v73, 0, v217
	s_waitcnt vmcnt(0)
	s_add_i32 s10, 0, 0x18000
	v_and_b32_e32 v74, 63, v70
	s_cmp_lg_u32 0, -1
	s_mov_b32 s12, 0
	s_mov_b32 s13, s12
	v_and_b32_e32 v178, 0xffffffe0, v49
	s_waitcnt vmcnt(11)
	ds_write_b128 v72, v[0:3]
	s_waitcnt vmcnt(10)
	ds_write_b128 v73, v[4:7]
	v_add_u32_e32 v0, 0, v214
	s_waitcnt vmcnt(9)
	ds_write_b128 v0, v[8:11] offset:49152
	v_lshlrev_b32_e32 v0, 8, v19
	v_lshlrev_b32_e32 v8, 8, v208
	v_and_b32_e32 v9, 0x70, v50
	v_bitop3_b32 v219, v23, v0, v20 bitop3:0xde
	v_xor_b32_e32 v219, v219, v252
	v_bitop3_b32 v220, v96, v8, v9 bitop3:0xde
	v_xor_b32_e32 v220, v220, v253
	v_add_u32_e32 v0, 0, v219
	v_add_u32_e32 v4, 0, v220
	s_waitcnt vmcnt(8)
	ds_write_b128 v0, v[12:15] offset:49152
	s_waitcnt lgkmcnt(0)
	s_barrier
	ds_read_b128 v[0:3], v4 offset:49152
	ds_read_b128 v[4:7], v4 offset:57344
	s_waitcnt vmcnt(7) lgkmcnt(1)
	v_mfma_f32_32x32x16_bf16 v[16:31], v[0:3], v[126:129], 0
	v_or_b32_e32 v0, 32, v96
	v_bitop3_b32 v222, v0, v8, v9 bitop3:0xde
	v_xor_b32_e32 v222, v222, v253
	v_ashrrev_i32_e32 v49, 31, v48
	s_mov_b32 s14, s12
	s_mov_b32 s15, s12
	s_mov_b32 s16, s12
	s_mov_b32 s17, s12
	s_waitcnt lgkmcnt(0)
	v_mfma_f32_32x32x16_bf16 v[32:47], v[4:7], v[126:129], 0
	v_add_u32_e32 v4, 0, v222
	ds_read_b128 v[0:3], v4 offset:49152
	ds_read_b128 v[4:7], v4 offset:57344
	s_mov_b32 s18, s12
	s_mov_b32 s19, s12
	s_mov_b32 s20, s12
	s_mov_b32 s21, s12
	s_mov_b32 s22, s12
	s_waitcnt vmcnt(6) lgkmcnt(1)
	v_mfma_f32_32x32x16_bf16 v[16:31], v[0:3], v[122:125], v[16:31]
	v_or_b32_e32 v0, 64, v96
	v_bitop3_b32 v221, v0, v8, v9 bitop3:0xde
	v_xor_b32_e32 v221, v221, v253
	s_mov_b32 s23, s12
	s_mov_b32 s24, s12
	s_mov_b32 s25, s12
	s_mov_b32 s26, s12
	s_mov_b32 s27, s12
	s_waitcnt lgkmcnt(0)
	v_mfma_f32_32x32x16_bf16 v[32:47], v[4:7], v[122:125], v[32:47]
	v_add_u32_e32 v4, 0, v221
	ds_read_b128 v[0:3], v4 offset:49152
	ds_read_b128 v[4:7], v4 offset:57344
	s_mov_b32 s38, 2
	v_mov_b32_e32 v210, 0
	s_waitcnt vmcnt(5) lgkmcnt(1)
	v_mfma_f32_32x32x16_bf16 v[16:31], v[0:3], v[118:121], v[16:31]
	v_or_b32_e32 v0, 0x60, v96
	v_bitop3_b32 v218, v0, v8, v9 bitop3:0xde
	v_xor_b32_e32 v218, v218, v253
	s_waitcnt lgkmcnt(0)
	v_mfma_f32_32x32x16_bf16 v[32:47], v[4:7], v[118:121], v[32:47]
	v_add_u32_e32 v4, 0, v218
	ds_read_b128 v[0:3], v4 offset:49152
	ds_read_b128 v[4:7], v4 offset:57344
	s_waitcnt vmcnt(4) lgkmcnt(1)
; #define SLOAD(i, k0) do { sv0[i] = *(const bf16x8*)(&Vh[(long)((k0) + sr) * LDK + sc]); sv1[i] = *(const bf16x8*)(&Vh[(long)((k0) + 32 + sr) * LDK + sc]); \
;     sk0[i] = *(const bf16x8*)(&Kh[(long)((k0) + sr) * LDK + sc]); sk1[i] = *(const bf16x8*)(&Kh[(long)((k0) + 32 + sr) * LDK + sc]); } while (0)
; #define SWRITE(off, i) do { *(bf16x8*)((char*)V_lds + (off) + vst0) = sv0[i];          \
;     *(bf16x8*)((char*)V_lds + (off) + vst1) = sv1[i]; int kc = sc * 2;               \
;     *(bf16x8*)((char*)K_lds + (off) + KSWZ(sr, kc)) = sk0[i];                       \
;     *(bf16x8*)((char*)K_lds + (off) + KSWZ(32 + sr, kc)) = sk1[i]; } while (0)
; #define SWAIT() asm volatile("s_waitcnt vmcnt(4)" ::: "memory")
; __device__ __forceinline__ void attn_dense_body(const bf16_t* __restrict__ Qb, const bf16_t* __restrict__ Kh, const bf16_t* __restrict__ Vh,
;                                                 bf16_t* __restrict__ Ob, int seq, char* lds, int dry) {
;     ...
;     SLOAD(0, 0); asm volatile("s_waitcnt vmcnt(0)" ::: "memory"); SWRITE(0, 0); __syncthreads();
;     qkt(pA0, pA1, K_lds, qr, r32, hi); partialSM(pA0, pA1, m_reg, mnA, alA);
;     SLOAD(1, KVBLK); if (2 < NT) SLOAD(0, 2 * KVBLK);
;     SWAIT(); SWRITE((int)SHM_K, 1); __syncthreads();
	v_mfma_f32_32x32x16_bf16 v[16:31], v[0:3], v[114:117], v[16:31]
	v_or_b32_e32 v0, 0x80, v96
	v_bitop3_b32 v215, v0, v8, v9 bitop3:0xde
	v_xor_b32_e32 v215, v215, v253
	s_waitcnt lgkmcnt(0)
	v_mfma_f32_32x32x16_bf16 v[32:47], v[4:7], v[114:117], v[32:47]
	v_add_u32_e32 v4, 0, v215
	ds_read_b128 v[0:3], v4 offset:49152
	ds_read_b128 v[4:7], v4 offset:57344
	s_waitcnt vmcnt(3) lgkmcnt(1)
	v_mfma_f32_32x32x16_bf16 v[16:31], v[0:3], v[110:113], v[16:31]
	v_or_b32_e32 v0, 0xa0, v96
	v_bitop3_b32 v213, v0, v8, v9 bitop3:0xde
	v_xor_b32_e32 v213, v213, v253
	s_waitcnt lgkmcnt(0)
	v_mfma_f32_32x32x16_bf16 v[32:47], v[4:7], v[110:113], v[32:47]
	v_add_u32_e32 v4, 0, v213
	ds_read_b128 v[0:3], v4 offset:49152
	v_and_b32_e32 v5, 0x3fffffc0, v70
	v_lshl_add_u32 v179, v5, 2, s10
	ds_read_b128 v[4:7], v4 offset:57344
	v_lshl_add_u32 v209, v208, 2, v179
	s_waitcnt vmcnt(2) lgkmcnt(1)
	v_mfma_f32_32x32x16_bf16 v[16:31], v[0:3], v[106:109], v[16:31]
	v_lshlrev_b32_e32 v0, 3, v74
	v_and_b32_e32 v1, 0xc0, v50
	v_and_or_b32 v10, v0, 24, v1
	v_lshlrev_b32_e32 v1, 1, v70
	v_and_b32_e32 v12, 0x100, v0
	v_add_u32_e32 v0, 64, v48
	v_and_b32_e32 v11, 32, v1
	s_waitcnt lgkmcnt(0)
	v_mfma_f32_32x32x16_bf16 v[32:47], v[4:7], v[106:109], v[32:47]
	v_or_b32_e32 v6, 0xc0, v96
	v_mad_i64_i32 v[0:1], s[10:11], v0, s71, 0
	v_add_u32_e32 v2, 0x60, v48
	v_or_b32_e32 v0, v0, v71
	v_mad_i64_i32 v[2:3], s[10:11], v2, s71, 0
	v_bitop3_b32 v223, v6, v8, v9 bitop3:0xde
	v_xor_b32_e32 v223, v223, v253
	v_lshl_add_u64 v[0:1], v[0:1], 1, s[6:7]
	v_or_b32_e32 v2, v2, v71
	v_add_u32_e32 v6, 0, v223
	global_load_dwordx4 v[50:53], v[0:1], off offset:2560
	global_load_dwordx4 v[58:61], v[0:1], off offset:2048
	v_lshl_add_u64 v[4:5], v[2:3], 1, s[6:7]
	ds_read_b128 v[0:3], v6 offset:49152
	s_waitcnt vmcnt(3) lgkmcnt(0)
	v_mfma_f32_32x32x16_bf16 v[16:31], v[0:3], v[102:105], v[16:31]
	v_or_b32_e32 v0, 0xe0, v96
	v_bitop3_b32 v224, v0, v8, v9 bitop3:0xde
	v_xor_b32_e32 v224, v224, v253
	global_load_dwordx4 v[54:57], v[4:5], off offset:2560
	global_load_dwordx4 v[62:65], v[4:5], off offset:2048
	v_or3_b32 v4, v10, v11, v12
	s_cselect_b32 s10, 0, 0
	v_add_u32_e32 v8, 0, v224
	v_add_u32_e32 v212, s10, v4
	ds_read_b128 v[4:7], v6 offset:57344
	ds_read_b128 v[0:3], v8 offset:49152
	ds_read_b128 v[66:69], v8 offset:57344
	s_waitcnt lgkmcnt(2)
	v_mfma_f32_32x32x16_bf16 v[32:47], v[4:7], v[102:105], v[32:47]
	s_waitcnt vmcnt(4) lgkmcnt(1)
	v_mfma_f32_32x32x16_bf16 v[16:31], v[0:3], v[98:101], v[16:31]
	v_mov_b64_e32 v[0:1], s[12:13]
	v_mov_b64_e32 v[2:3], s[14:15]
	v_mov_b64_e32 v[4:5], s[16:17]
	v_mov_b64_e32 v[6:7], s[18:19]
	v_mov_b64_e32 v[8:9], s[20:21]
	v_mov_b64_e32 v[10:11], s[22:23]
	v_mov_b64_e32 v[12:13], s[24:25]
	s_waitcnt lgkmcnt(0)
	v_mfma_f32_32x32x16_bf16 v[32:47], v[66:69], v[98:101], v[32:47]
	s_nop 2
	v_max_f32_e32 v66, v17, v17
	v_max_f32_e32 v67, v16, v16
	v_max_f32_e32 v66, v67, v66
	v_max3_f32 v66, v66, v18, v19
	v_max3_f32 v66, v66, v20, v21
	v_max3_f32 v66, v66, v22, v23
	v_max3_f32 v66, v66, v24, v25
	v_max3_f32 v66, v66, v26, v27
	v_max3_f32 v66, v66, v28, v29
	v_max3_f32 v66, v66, v30, v31
	v_max3_f32 v66, v66, v32, v33
	v_max3_f32 v66, v66, v34, v35
	v_max3_f32 v66, v66, v36, v37
	v_max3_f32 v66, v66, v38, v39
	v_max3_f32 v66, v66, v40, v41
	v_max3_f32 v66, v66, v42, v43
	v_max3_f32 v66, v66, v44, v45
	v_max3_f32 v75, v66, v46, v47
	v_mov_b32_e32 v66, v75
	s_nop 1
	v_permlane32_swap_b32_e32 v75, v66
	v_max_f32_e32 v76, v66, v66
	v_add_u32_e32 v66, 0xa0, v48
	v_mad_i64_i32 v[66:67], s[10:11], v66, s71, 0
	v_add_u32_e32 v68, 0x80, v48
	v_or_b32_e32 v66, v66, v71
	v_mad_i64_i32 v[68:69], s[10:11], v68, s71, 0
	v_lshl_add_u64 v[66:67], v[66:67], 1, s[6:7]
	v_or_b32_e32 v68, v68, v71
	v_lshl_add_u64 v[68:69], v[68:69], 1, s[6:7]
	global_load_dwordx4 v[130:133], v[66:67], off offset:2048
	global_load_dwordx4 v[142:145], v[66:67], off offset:2560
	global_load_dwordx4 v[138:141], v[68:69], off offset:2048
	global_load_dwordx4 v[134:137], v[68:69], off offset:2560
	v_max_f32_e32 v66, v75, v75
	v_max_f32_e32 v66, v66, v76
	v_add_f32_e32 v67, 0x7149f2ca, v66
	s_add_i32 s6, 0, 0x10000
	v_cmp_ge_f32_e32 vcc, s72, v67
	s_waitcnt vmcnt(4)
	s_waitcnt vmcnt(7)
	ds_write_b128 v72, v[50:53] offset:16384
	s_waitcnt vmcnt(5)
	ds_write_b128 v73, v[54:57] offset:16384
	v_add_u32_e32 v50, s6, v214
	ds_write_b128 v50, v[58:61]
	v_add_u32_e32 v50, s6, v219
	s_cmp_eq_u64 vcc, exec
	s_waitcnt vmcnt(4)
; #define SBAR() __builtin_amdgcn_sched_barrier(0)
; #define SLOAD(i, k0) do { sv0[i] = *(const bf16x8*)(&Vh[(long)((k0) + sr) * LDK + sc]); sv1[i] = *(const bf16x8*)(&Vh[(long)((k0) + 32 + sr) * LDK + sc]); \
;     sk0[i] = *(const bf16x8*)(&Kh[(long)((k0) + sr) * LDK + sc]); sk1[i] = *(const bf16x8*)(&Kh[(long)((k0) + 32 + sr) * LDK + sc]); } while (0)
; #define SWRITE(off, i) do { *(bf16x8*)((char*)V_lds + (off) + vst0) = sv0[i];          \
;     *(bf16x8*)((char*)V_lds + (off) + vst1) = sv1[i]; int kc = sc * 2;               \
;     *(bf16x8*)((char*)K_lds + (off) + KSWZ(sr, kc)) = sk0[i];                       \
;     *(bf16x8*)((char*)K_lds + (off) + KSWZ(32 + sr, kc)) = sk1[i]; } while (0)
; #define SWAIT() asm volatile("s_waitcnt vmcnt(4)" ::: "memory")
; __device__ __forceinline__ void attn_dense_body(const bf16_t* __restrict__ Qb, const bf16_t* __restrict__ Kh, const bf16_t* __restrict__ Vh,
;                                                 bf16_t* __restrict__ Ob, int seq, char* lds, int dry) {
;     ...
;     qkt(pA0, pA1, K_lds, qr, r32, hi); partialSM(pA0, pA1, m_reg, mnA, alA);
;     SLOAD(1, KVBLK); if (2 < NT) SLOAD(0, 2 * KVBLK);
;     SWAIT(); SWRITE((int)SHM_K, 1); __syncthreads();
;     int oq = (int)SHM_K, ov = 0, ow = 2 * (int)SHM_K;
;     for (int j = 1; j + 1 < NT; j += 2) {
;         SBAR(); qkt(pB0, pB1, (bf16_t*)((char*)K_lds + oq), qr, r32, hi);
;         finishSM(pA0, pA1, alA, l_reg, pa0, pa1, pa2, pa3); SBAR();
	ds_write_b128 v50, v[62:65]
	v_max_f32_e32 v50, 0xf149f2ca, v66
	s_cselect_b64 vcc, -1, 0
	v_cndmask_b32_e32 v166, v50, v198, vcc
	v_sub_f32_e32 v51, 0xf149f2ca, v50
	v_mul_f32_e32 v50, 0xbe0293ee, v166
	v_fmamk_f32 v16, v16, 0x3e0293ee, v50
	v_mov_b32_e32 v163, v16
	v_fmamk_f32 v16, v17, 0x3e0293ee, v50
	v_mov_b32_e32 v177, v16
	v_fmamk_f32 v16, v18, 0x3e0293ee, v50
	v_mov_b32_e32 v164, v16
	v_fmamk_f32 v16, v19, 0x3e0293ee, v50
	v_exp_f32_e32 v229, v16
	v_fmamk_f32 v16, v20, 0x3e0293ee, v50
	v_mov_b32_e32 v176, v16
	v_fmamk_f32 v16, v21, 0x3e0293ee, v50
	v_exp_f32_e32 v230, v16
	v_fmamk_f32 v16, v22, 0x3e0293ee, v50
	v_mov_b32_e32 v165, v16
	v_fmamk_f32 v16, v23, 0x3e0293ee, v50
	v_mov_b32_e32 v175, v16
	v_fmamk_f32 v16, v24, 0x3e0293ee, v50
	v_mov_b32_e32 v171, v16
	v_fmamk_f32 v16, v25, 0x3e0293ee, v50
	v_mov_b32_e32 v173, v16
	v_fmamk_f32 v16, v26, 0x3e0293ee, v50
	v_mul_f32_e32 v51, 0x3e0293ee, v51
	v_mov_b32_e32 v172, v16
	v_fmamk_f32 v16, v27, 0x3e0293ee, v50
	v_exp_f32_e32 v51, v51
	v_mov_b32_e32 v174, v16
	v_fmamk_f32 v16, v28, 0x3e0293ee, v50
	v_mov_b32_e32 v167, v16
	v_fmamk_f32 v16, v29, 0x3e0293ee, v50
	v_mov_b32_e32 v169, v16
	v_fmamk_f32 v16, v30, 0x3e0293ee, v50
	v_mov_b64_e32 v[14:15], s[26:27]
	s_mov_b32 s20, 0x3e0293ee
	v_mov_b32_e32 v168, v16
	v_lshl_add_u64 v[16:17], v[48:49], 0, s[8:9]
	v_pk_fma_f32 v[146:147], v[46:47], s[20:21], v[50:51] op_sel_hi:[1,0,0]
	v_pk_fma_f32 v[148:149], v[44:45], s[20:21], v[50:51] op_sel_hi:[1,0,0]
	v_pk_fma_f32 v[150:151], v[42:43], s[20:21], v[50:51] op_sel_hi:[1,0,0]
	v_pk_fma_f32 v[152:153], v[40:41], s[20:21], v[50:51] op_sel_hi:[1,0,0]
	v_pk_fma_f32 v[154:155], v[38:39], s[20:21], v[50:51] op_sel_hi:[1,0,0]
	v_pk_fma_f32 v[156:157], v[36:37], s[20:21], v[50:51] op_sel_hi:[1,0,0]
	v_pk_fma_f32 v[158:159], v[34:35], s[20:21], v[50:51] op_sel_hi:[1,0,0]
	v_pk_fma_f32 v[160:161], v[32:33], s[20:21], v[50:51] op_sel_hi:[1,0,0]
	v_fmac_f32_e32 v50, 0x3e0293ee, v31
	v_mad_u64_u32 v[18:19], s[8:9], v16, s70, 0
	v_and_b32_e32 v16, 15, v70
	v_mov_b32_e32 v170, v50
	v_lshlrev_b32_e32 v16, 4, v16
	v_mad_i32_i24 v17, v17, s70, v19
	v_or3_b32 v16, v18, s39, v16
	v_cndmask_b32_e64 v225, v51, 1.0, vcc
	v_lshl_add_u64 v[180:181], s[2:3], 0, v[16:17]
	v_mov_b64_e32 v[62:63], v[14:15]
	v_mov_b64_e32 v[46:47], v[14:15]
	v_mov_b64_e32 v[30:31], v[14:15]
	v_cmp_gt_u32_e64 s[6:7], 32, v74
	s_mov_b32 s8, 0x8000
	v_mov_b64_e32 v[60:61], v[12:13]
	v_mov_b64_e32 v[58:59], v[10:11]
	v_mov_b64_e32 v[56:57], v[8:9]
	v_mov_b64_e32 v[54:55], v[6:7]
	v_mov_b64_e32 v[52:53], v[4:5]
	v_mov_b64_e32 v[50:51], v[2:3]
	v_mov_b64_e32 v[48:49], v[0:1]
	v_mov_b64_e32 v[44:45], v[12:13]
	v_mov_b64_e32 v[42:43], v[10:11]
	v_mov_b64_e32 v[40:41], v[8:9]
	v_mov_b64_e32 v[38:39], v[6:7]
	v_mov_b64_e32 v[36:37], v[4:5]
	v_mov_b64_e32 v[34:35], v[2:3]
	v_mov_b64_e32 v[32:33], v[0:1]
	v_mov_b64_e32 v[28:29], v[12:13]
	v_mov_b64_e32 v[26:27], v[10:11]
	v_mov_b64_e32 v[24:25], v[8:9]
	v_mov_b64_e32 v[22:23], v[6:7]
	v_mov_b64_e32 v[20:21], v[4:5]
	v_mov_b64_e32 v[18:19], v[2:3]
	v_mov_b64_e32 v[16:17], v[0:1]
	v_exp_f32_e32 v146, v146
	v_exp_f32_e32 v147, v147
	v_exp_f32_e32 v148, v148
	v_exp_f32_e32 v149, v149
	v_exp_f32_e32 v150, v150
	v_exp_f32_e32 v151, v151
	v_exp_f32_e32 v152, v152
	v_exp_f32_e32 v153, v153
	v_exp_f32_e32 v154, v154
	v_exp_f32_e32 v155, v155
	v_exp_f32_e32 v156, v156
	v_exp_f32_e32 v157, v157
	v_exp_f32_e32 v158, v158
	v_exp_f32_e32 v159, v159
	v_exp_f32_e32 v160, v160
	v_exp_f32_e32 v161, v161
	s_waitcnt lgkmcnt(0)
	s_barrier
.LBB0_269:
	s_mov_b32 s13, s12
	s_mov_b32 s12, s8
	s_add_i32 s8, s37, 0
	v_add_u32_e32 v71, s8, v220
	ds_read_b128 v[64:67], v71 offset:49152
	ds_read_b128 v[68:71], v71 offset:57344
	v_add_u32_e32 v239, s8, v222
	ds_read_b128 v[232:235], v239 offset:49152
	ds_read_b128 v[236:239], v239 offset:57344
	v_add_u32_e32 v247, s8, v221
	ds_read_b128 v[240:243], v247 offset:49152
	ds_read_b128 v[244:247], v247 offset:57344
	s_waitcnt lgkmcnt(5)
	v_mfma_f32_32x32x16_bf16 v[80:95], v[64:67], v[126:129], 0
	v_exp_f32_e32 v163, v163
	v_exp_f32_e32 v177, v177
	v_exp_f32_e32 v164, v164
	v_exp_f32_e32 v176, v176
	v_exp_f32_e32 v165, v165
	s_waitcnt lgkmcnt(4)
	v_mfma_f32_32x32x16_bf16 v[64:79], v[68:71], v[126:129], 0
	v_exp_f32_e32 v175, v175
	v_exp_f32_e32 v171, v171
	v_exp_f32_e32 v173, v173
	v_exp_f32_e32 v172, v172
	v_exp_f32_e32 v174, v174
	s_waitcnt lgkmcnt(3)
	v_mfma_f32_32x32x16_bf16 v[80:95], v[232:235], v[122:125], v[80:95]
	v_exp_f32_e32 v167, v167
	v_exp_f32_e32 v169, v169
	v_exp_f32_e32 v168, v168
	v_exp_f32_e32 v170, v170
	v_add_f32_e32 v162, 0, v163
	s_waitcnt lgkmcnt(2)
	v_mfma_f32_32x32x16_bf16 v[64:79], v[236:239], v[122:125], v[64:79]
	v_add_u32_e32 v239, s8, v218
	ds_read_b128 v[232:235], v239 offset:49152
	ds_read_b128 v[236:239], v239 offset:57344
	v_add_f32_e32 v162, v177, v162
	v_add_f32_e32 v162, v164, v162
	v_add_f32_e32 v162, v229, v162
	v_add_f32_e32 v162, v176, v162
	v_add_f32_e32 v162, v230, v162
	s_waitcnt lgkmcnt(3)
	v_mfma_f32_32x32x16_bf16 v[80:95], v[240:243], v[118:121], v[80:95]
	v_add_f32_e32 v162, v165, v162
	v_add_f32_e32 v162, v175, v162
	v_add_f32_e32 v162, v171, v162
	v_add_f32_e32 v162, v173, v162
	v_add_f32_e32 v162, v172, v162
	s_waitcnt lgkmcnt(2)
	v_mfma_f32_32x32x16_bf16 v[64:79], v[244:247], v[118:121], v[64:79]
	v_add_u32_e32 v247, s8, v215
	ds_read_b128 v[240:243], v247 offset:49152
	ds_read_b128 v[244:247], v247 offset:57344
	v_add_f32_e32 v162, v174, v162
	v_add_f32_e32 v162, v167, v162
	v_add_f32_e32 v162, v169, v162
	v_add_f32_e32 v162, v168, v162
	v_add_f32_e32 v162, v170, v162
	s_waitcnt lgkmcnt(3)
; #define SBAR() __builtin_amdgcn_sched_barrier(0)
; #define SLOAD(i, k0) do { sv0[i] = *(const bf16x8*)(&Vh[(long)((k0) + sr) * LDK + sc]); sv1[i] = *(const bf16x8*)(&Vh[(long)((k0) + 32 + sr) * LDK + sc]); \
;     sk0[i] = *(const bf16x8*)(&Kh[(long)((k0) + sr) * LDK + sc]); sk1[i] = *(const bf16x8*)(&Kh[(long)((k0) + 32 + sr) * LDK + sc]); } while (0)
; #define SWRITE(off, i) do { *(bf16x8*)((char*)V_lds + (off) + vst0) = sv0[i];          \
;     *(bf16x8*)((char*)V_lds + (off) + vst1) = sv1[i]; int kc = sc * 2;               \
;     *(bf16x8*)((char*)K_lds + (off) + KSWZ(sr, kc)) = sk0[i];                       \
;     *(bf16x8*)((char*)K_lds + (off) + KSWZ(32 + sr, kc)) = sk1[i]; } while (0)
; #define SWAIT() asm volatile("s_waitcnt vmcnt(4)" ::: "memory")
; __device__ __forceinline__ void attn_dense_body(const bf16_t* __restrict__ Qb, const bf16_t* __restrict__ Kh, const bf16_t* __restrict__ Vh,
;                                                 bf16_t* __restrict__ Ob, int seq, char* lds, int dry) {
;     ...
;         SBAR(); qkt(pB0, pB1, (bf16_t*)((char*)K_lds + oq), qr, r32, hi);
;         finishSM(pA0, pA1, alA, l_reg, pa0, pa1, pa2, pa3); SBAR();
;         SLOAD(1, (j + 2) * KVBLK); SBAR();
;         pv_d0(o, vb0 + ov, pa0, pa1, pa2, pa3); partialSM(pB0, pB1, m_reg, mnB, alB);
;         SWAIT(); SWRITE(ow, 0);
	v_mfma_f32_32x32x16_bf16 v[80:95], v[232:235], v[114:117], v[80:95]
	v_add_f32_e32 v162, v160, v162
	v_add_f32_e32 v162, v161, v162
	v_add_f32_e32 v162, v158, v162
	v_add_f32_e32 v162, v159, v162
	v_add_f32_e32 v162, v156, v162
	s_waitcnt lgkmcnt(2)
	v_mfma_f32_32x32x16_bf16 v[64:79], v[236:239], v[114:117], v[64:79]
	v_add_u32_e32 v239, s8, v213
	ds_read_b128 v[232:235], v239 offset:49152
	ds_read_b128 v[236:239], v239 offset:57344
	v_add_f32_e32 v162, v157, v162
	v_add_f32_e32 v162, v154, v162
	v_add_f32_e32 v162, v155, v162
	v_add_f32_e32 v162, v152, v162
	v_add_f32_e32 v162, v153, v162
	s_waitcnt lgkmcnt(3)
	v_mfma_f32_32x32x16_bf16 v[80:95], v[240:243], v[110:113], v[80:95]
	v_add_f32_e32 v162, v150, v162
	v_add_f32_e32 v162, v151, v162
	v_add_f32_e32 v162, v148, v162
	v_add_f32_e32 v162, v149, v162
	s_waitcnt lgkmcnt(2)
	v_mfma_f32_32x32x16_bf16 v[64:79], v[244:247], v[110:113], v[64:79]
	v_add_u32_e32 v247, s8, v223
	ds_read_b128 v[240:243], v247 offset:49152
	ds_read_b128 v[244:247], v247 offset:57344
	v_add_f32_e32 v162, v146, v162
	v_add_f32_e32 v226, v147, v162
	v_mov_b32_e32 v227, v226
	v_cvt_pk_bf16_f32 v162, v163, v177
	s_waitcnt lgkmcnt(3)
	v_mfma_f32_32x32x16_bf16 v[80:95], v[232:235], v[106:109], v[80:95]
	v_cvt_pk_bf16_f32 v163, v164, v229
	v_cvt_pk_bf16_f32 v164, v176, v230
	v_cvt_pk_bf16_f32 v165, v165, v175
	v_cvt_pk_bf16_f32 v228, v171, v173
	s_waitcnt lgkmcnt(2)
	v_mfma_f32_32x32x16_bf16 v[64:79], v[236:239], v[106:109], v[64:79]
	v_add_u32_e32 v239, s8, v224
	ds_read_b128 v[232:235], v239 offset:49152
	ds_read_b128 v[236:239], v239 offset:57344
	v_cvt_pk_bf16_f32 v229, v172, v174
	v_cvt_pk_bf16_f32 v230, v167, v169
	v_permlane32_swap_b32_e32 v226, v227
	v_permlane32_swap_b32_e32 v162, v164
	s_waitcnt lgkmcnt(3)
	v_mfma_f32_32x32x16_bf16 v[80:95], v[240:243], v[102:105], v[80:95]
	v_cvt_pk_bf16_f32 v231, v168, v170
	v_permlane32_swap_b32_e32 v228, v230
	v_cvt_pk_bf16_f32 v168, v160, v161
	v_cvt_pk_bf16_f32 v169, v158, v159
	s_waitcnt lgkmcnt(2)
	v_mfma_f32_32x32x16_bf16 v[64:79], v[244:247], v[102:105], v[64:79]
	v_cvt_pk_bf16_f32 v170, v156, v157
	v_cvt_pk_bf16_f32 v171, v154, v155
	v_cvt_pk_bf16_f32 v172, v152, v153
	v_cvt_pk_bf16_f32 v173, v150, v151
	s_waitcnt lgkmcnt(1)
	v_mfma_f32_32x32x16_bf16 v[80:95], v[232:235], v[98:101], v[80:95]
	v_cvt_pk_bf16_f32 v174, v148, v149
	v_cvt_pk_bf16_f32 v175, v146, v147
	v_permlane32_swap_b32_e32 v163, v165
	v_permlane32_swap_b32_e32 v229, v231
	s_waitcnt lgkmcnt(0)
	v_mfma_f32_32x32x16_bf16 v[64:79], v[236:239], v[98:101], v[64:79]
	v_permlane32_swap_b32_e32 v168, v170
	v_permlane32_swap_b32_e32 v169, v171
	v_permlane32_swap_b32_e32 v172, v174
	v_permlane32_swap_b32_e32 v173, v175
	s_mov_b32 s8, 0xfffb8000
	v_add_co_u32_e32 v150, vcc, s8, v180
	s_mov_b32 s8, 0xfffd0000
	s_nop 0
	v_addc_co_u32_e32 v151, vcc, -1, v181, vcc
	v_add_co_u32_e32 v154, vcc, s8, v180
	s_nop 1
	v_addc_co_u32_e32 v155, vcc, -1, v181, vcc
	global_load_dwordx4 v[146:149], v[150:151], off
	s_nop 0
	global_load_dwordx4 v[150:153], v[150:151], off offset:-512
	s_nop 0
	global_load_dwordx4 v[158:161], v[154:155], off
	s_nop 0
	global_load_dwordx4 v[154:157], v[154:155], off offset:-512
	v_add_u32_e32 v211, s13, v212
	ds_read_b64_tr_b16 v[232:233], v211 offset:0x0
	ds_read_b64_tr_b16 v[234:235], v211 offset:0x800
	ds_read_b64_tr_b16 v[236:237], v211 offset:0x1000
	ds_read_b64_tr_b16 v[238:239], v211 offset:0x1800
	ds_read_b64_tr_b16 v[240:241], v211 offset:0x2000
	ds_read_b64_tr_b16 v[242:243], v211 offset:0x2800
	ds_read_b64_tr_b16 v[244:245], v211 offset:0x3000
	ds_read_b64_tr_b16 v[246:247], v211 offset:0x3800
	s_waitcnt lgkmcnt(0)
	s_nop 0
	v_mfma_f32_32x32x16_bf16 v[0:15], v[162:165], v[232:235], v[0:15]
	ds_read_b64_tr_b16 v[232:233], v211 offset:0x200
	ds_read_b64_tr_b16 v[234:235], v211 offset:0xa00
	s_add_i32 s14, s12, 0
	s_waitcnt vmcnt(4)
	v_add_u32_e32 v253, s14, v216
	ds_write_b128 v253, v[134:137]
	v_max_f32_e32 v248, v81, v81
	v_max_f32_e32 v249, v80, v80
	v_max_f32_e32 v248, v249, v248
	v_max3_f32 v248, v248, v82, v83
	v_max3_f32 v248, v248, v84, v85
	v_mfma_f32_32x32x16_bf16 v[0:15], v[228:231], v[236:239], v[0:15]
	ds_read_b64_tr_b16 v[236:237], v211 offset:0x1200
	ds_read_b64_tr_b16 v[238:239], v211 offset:0x1a00
	v_add_u32_e32 v253, s14, v217
	ds_write_b128 v253, v[142:145]
	v_max3_f32 v248, v248, v86, v87
	v_max3_f32 v248, v248, v88, v89
	v_max3_f32 v248, v248, v90, v91
	v_max3_f32 v248, v248, v92, v93
	v_max3_f32 v248, v248, v94, v95
	v_mfma_f32_32x32x16_bf16 v[0:15], v[168:171], v[240:243], v[0:15]
	ds_read_b64_tr_b16 v[240:241], v211 offset:0x2200
	ds_read_b64_tr_b16 v[242:243], v211 offset:0x2a00
	v_add_u32_e32 v253, s14, v214
	ds_write_b128 v253, v[138:141] offset:49152
	v_max3_f32 v248, v248, v64, v65
	v_max3_f32 v248, v248, v66, v67
	v_max3_f32 v248, v248, v68, v69
	v_max3_f32 v248, v248, v70, v71
	v_max3_f32 v248, v248, v72, v73
	v_mfma_f32_32x32x16_bf16 v[0:15], v[172:175], v[244:247], v[0:15]
	ds_read_b64_tr_b16 v[244:245], v211 offset:0x3200
	ds_read_b64_tr_b16 v[246:247], v211 offset:0x3a00
	v_add_u32_e32 v253, s14, v219
	ds_write_b128 v253, v[130:133] offset:49152
	v_max3_f32 v248, v248, v74, v75
	v_max3_f32 v248, v248, v76, v77
	v_max3_f32 v248, v248, v78, v79
	v_mov_b32_e32 v249, v248
	s_waitcnt lgkmcnt(0)
; #define SWRITE(off, i) do { *(bf16x8*)((char*)V_lds + (off) + vst0) = sv0[i];          \
;     *(bf16x8*)((char*)V_lds + (off) + vst1) = sv1[i]; int kc = sc * 2;               \
;     *(bf16x8*)((char*)K_lds + (off) + KSWZ(sr, kc)) = sk0[i];                       \
;     *(bf16x8*)((char*)K_lds + (off) + KSWZ(32 + sr, kc)) = sk1[i]; } while (0)
; #define SWAIT() asm volatile("s_waitcnt vmcnt(4)" ::: "memory")
; #define RESC(a) do { if (__any((a) < 1.f)) { if (hi == 0) al_l[r32] = (a); asm volatile("s_waitcnt lgkmcnt(0)" ::: "memory"); \
;     _Pragma("unroll") for (int d = 0; d < 4; ++d) _Pragma("unroll") for (int r = 0; r < 16; ++r) o[d][r] *= al_l[crow(r, hi)]; } } while (0)
; __device__ __forceinline__ void partialSM(f32x16& p0, f32x16& p1, float& m_reg, float& mn, float& alpha) {
;     constexpr float C = SCALE * 1.4426950408889634f;
;     float pmax = p0[0];
; #pragma unroll
;     for (int r = 1; r < 16; ++r) pmax = fmaxf(pmax, p0[r]);
; #pragma unroll
;     for (int r = 0; r < 16; ++r) pmax = fmaxf(pmax, p1[r]);
;     { auto rr = __builtin_amdgcn_permlane32_swap(__float_as_uint(pmax), __float_as_uint(pmax), false, false);
;       pmax = fmaxf(__uint_as_float(rr[0]), __uint_as_float(rr[1])); }
;     if (__builtin_expect(__all(pmax - m_reg <= THR / SCALE), 1)) { mn = m_reg; alpha = 1.f; }
;     else { mn = fmaxf(m_reg, pmax); alpha = __builtin_amdgcn_exp2f((m_reg - mn) * C); m_reg = mn; }
;     float mnC = -mn * C;
; #pragma unroll
;     for (int r = 0; r < 16; ++r) p0[r] = fmaf(p0[r], C, mnC);
; #pragma unroll
;     for (int r = 0; r < 16; ++r) p1[r] = fmaf(p1[r], C, mnC);
; __device__ __forceinline__ void attn_dense_body(const bf16_t* __restrict__ Qb, const bf16_t* __restrict__ Kh, const bf16_t* __restrict__ Vh,
;                                                 bf16_t* __restrict__ Ob, int seq, char* lds, int dry) {
;     ...
;         pv_d0(o, vb0 + ov, pa0, pa1, pa2, pa3); partialSM(pB0, pB1, m_reg, mnB, alB);
;         SWAIT(); SWRITE(ow, 0);
;         RESC(alB); __syncthreads();
	v_mfma_f32_32x32x16_bf16 v[48:63], v[162:165], v[232:235], v[48:63]
	ds_read_b64_tr_b16 v[232:233], v211 offset:0x400
	ds_read_b64_tr_b16 v[234:235], v211 offset:0xc00
	v_permlane32_swap_b32_e32 v248, v249
	v_max_f32_e32 v249, v249, v249
	v_max_f32_e32 v248, v248, v248
	v_max_f32_e32 v248, v248, v249
	v_mfma_f32_32x32x16_bf16 v[48:63], v[228:231], v[236:239], v[48:63]
	ds_read_b64_tr_b16 v[236:237], v211 offset:0x1400
	ds_read_b64_tr_b16 v[238:239], v211 offset:0x1c00
	v_sub_f32_e32 v249, v248, v166
	v_cmp_ge_f32_e32 vcc, s72, v249
	v_max_f32_e32 v249, v166, v166
	v_max_f32_e32 v248, v249, v248
	v_sub_f32_e32 v249, v166, v248
	v_mfma_f32_32x32x16_bf16 v[48:63], v[168:171], v[240:243], v[48:63]
	ds_read_b64_tr_b16 v[240:241], v211 offset:0x2400
	ds_read_b64_tr_b16 v[242:243], v211 offset:0x2c00
	v_mul_f32_e32 v249, 0x3e0293ee, v249
	v_exp_f32_e32 v249, v249
	v_mfma_f32_32x32x16_bf16 v[48:63], v[172:175], v[244:247], v[48:63]
	ds_read_b64_tr_b16 v[244:245], v211 offset:0x3400
	ds_read_b64_tr_b16 v[246:247], v211 offset:0x3c00
	s_cmp_eq_u64 vcc, exec
	s_cselect_b64 s[8:9], -1, 0
	s_nop 0
	v_cndmask_b32_e64 v167, v249, 1.0, s[8:9]
	v_cndmask_b32_e64 v176, v248, v166, s[8:9]
	v_mul_f32_e32 v177, 0xbe0293ee, v176
	s_waitcnt lgkmcnt(0)
	v_mfma_f32_32x32x16_bf16 v[32:47], v[162:165], v[232:235], v[32:47]
	ds_read_b64_tr_b16 v[232:233], v211 offset:0x600
	ds_read_b64_tr_b16 v[234:235], v211 offset:0xe00
	v_fmamk_f32 v250, v92, 0x3e0293ee, v177
	v_fmamk_f32 v251, v93, 0x3e0293ee, v177
	v_fmamk_f32 v252, v94, 0x3e0293ee, v177
	v_fmamk_f32 v253, v95, 0x3e0293ee, v177
	v_mfma_f32_32x32x16_bf16 v[32:47], v[228:231], v[236:239], v[32:47]
	ds_read_b64_tr_b16 v[236:237], v211 offset:0x1600
	ds_read_b64_tr_b16 v[238:239], v211 offset:0x1e00
	v_fmamk_f32 v248, v90, 0x3e0293ee, v177
	v_fmamk_f32 v249, v91, 0x3e0293ee, v177
	v_mfma_f32_32x32x16_bf16 v[32:47], v[168:171], v[240:243], v[32:47]
	ds_read_b64_tr_b16 v[240:241], v211 offset:0x2600
	ds_read_b64_tr_b16 v[242:243], v211 offset:0x2e00
	v_exp_f32_e32 v250, v250
	v_exp_f32_e32 v251, v251
	v_exp_f32_e32 v252, v252
	v_mfma_f32_32x32x16_bf16 v[32:47], v[172:175], v[244:247], v[32:47]
	ds_read_b64_tr_b16 v[244:245], v211 offset:0x3600
	ds_read_b64_tr_b16 v[246:247], v211 offset:0x3e00
	v_exp_f32_e32 v253, v253
	v_exp_f32_e32 v248, v248
	v_exp_f32_e32 v249, v249
	s_waitcnt lgkmcnt(0)
	v_mfma_f32_32x32x16_bf16 v[16:31], v[162:165], v[232:235], v[16:31]
	v_fmamk_f32 v232, v73, 0x3e0293ee, v177
	v_fmamk_f32 v233, v74, 0x3e0293ee, v177
	v_fmamk_f32 v234, v75, 0x3e0293ee, v177
	v_fmamk_f32 v235, v76, 0x3e0293ee, v177
	v_mfma_f32_32x32x16_bf16 v[16:31], v[228:231], v[236:239], v[16:31]
	v_fmamk_f32 v238, v80, 0x3e0293ee, v177
	v_fmamk_f32 v239, v81, 0x3e0293ee, v177
	v_fmamk_f32 v236, v77, 0x3e0293ee, v177
	v_fmamk_f32 v237, v78, 0x3e0293ee, v177
	v_fmamk_f32 v230, v71, 0x3e0293ee, v177
	v_fmamk_f32 v231, v72, 0x3e0293ee, v177
	v_mfma_f32_32x32x16_bf16 v[16:31], v[168:171], v[240:243], v[16:31]
	v_fmamk_f32 v240, v82, 0x3e0293ee, v177
	v_fmamk_f32 v241, v83, 0x3e0293ee, v177
	v_fmamk_f32 v242, v84, 0x3e0293ee, v177
	v_fmamk_f32 v243, v85, 0x3e0293ee, v177
	v_fmamk_f32 v170, v79, 0x3e0293ee, v177
	v_fmamk_f32 v171, v64, 0x3e0293ee, v177
	v_mfma_f32_32x32x16_bf16 v[16:31], v[172:175], v[244:247], v[16:31]
	v_fmamk_f32 v244, v86, 0x3e0293ee, v177
	v_fmamk_f32 v245, v87, 0x3e0293ee, v177
	v_fmamk_f32 v246, v88, 0x3e0293ee, v177
	v_fmamk_f32 v247, v89, 0x3e0293ee, v177
	v_fmamk_f32 v172, v65, 0x3e0293ee, v177
	v_fmamk_f32 v173, v66, 0x3e0293ee, v177
	v_fmamk_f32 v174, v67, 0x3e0293ee, v177
	v_fmamk_f32 v175, v68, 0x3e0293ee, v177
	v_mov_b32_e32 v228, v167
	s_nop 0
	v_cmp_gt_f32_e32 vcc, 1.0, v228
	s_cbranch_vccz .LBB0_273
	s_and_saveexec_b64 s[10:11], s[6:7]
	ds_write_b32 v209, v228 offset:128
	s_or_b64 exec, exec, s[10:11]
	s_waitcnt lgkmcnt(0)
	v_add_u32_e32 v163, v179, v96
	ds_read_b128 v[80:83], v163 offset:224
	ds_read_b128 v[84:87], v163 offset:192
	ds_read_b128 v[88:91], v163 offset:160
	ds_read_b128 v[92:95], v163 offset:128
	s_waitcnt lgkmcnt(3)
	v_pk_mul_f32 v[12:13], v[12:13], v[80:81]
	s_waitcnt lgkmcnt(2)
	v_pk_mul_f32 v[8:9], v[8:9], v[84:85]
	s_waitcnt lgkmcnt(1)
	v_pk_mul_f32 v[4:5], v[4:5], v[88:89]
	v_pk_mul_f32 v[14:15], v[14:15], v[82:83]
	v_pk_mul_f32 v[10:11], v[10:11], v[86:87]
	v_pk_mul_f32 v[6:7], v[6:7], v[90:91]
	s_waitcnt lgkmcnt(0)
	v_pk_mul_f32 v[2:3], v[2:3], v[94:95]
	v_pk_mul_f32 v[0:1], v[0:1], v[92:93]
	v_pk_mul_f32 v[60:61], v[60:61], v[80:81]
	v_pk_mul_f32 v[56:57], v[56:57], v[84:85]
	v_pk_mul_f32 v[52:53], v[52:53], v[88:89]
	v_pk_mul_f32 v[62:63], v[62:63], v[82:83]
	v_pk_mul_f32 v[58:59], v[58:59], v[86:87]
	v_pk_mul_f32 v[54:55], v[54:55], v[90:91]
	v_pk_mul_f32 v[50:51], v[50:51], v[94:95]
	v_pk_mul_f32 v[48:49], v[48:49], v[92:93]
	v_pk_mul_f32 v[44:45], v[44:45], v[80:81]
	v_pk_mul_f32 v[40:41], v[40:41], v[84:85]
	v_pk_mul_f32 v[36:37], v[36:37], v[88:89]
	v_pk_mul_f32 v[46:47], v[46:47], v[82:83]
	v_pk_mul_f32 v[42:43], v[42:43], v[86:87]
	v_pk_mul_f32 v[38:39], v[38:39], v[90:91]
	v_pk_mul_f32 v[34:35], v[34:35], v[94:95]
	v_pk_mul_f32 v[32:33], v[32:33], v[92:93]
	v_pk_mul_f32 v[28:29], v[28:29], v[80:81]
	v_pk_mul_f32 v[24:25], v[24:25], v[84:85]
	v_pk_mul_f32 v[20:21], v[20:21], v[88:89]
	v_pk_mul_f32 v[30:31], v[30:31], v[82:83]
	v_pk_mul_f32 v[26:27], v[26:27], v[86:87]
	v_pk_mul_f32 v[22:23], v[22:23], v[90:91]
	v_pk_mul_f32 v[18:19], v[18:19], v[94:95]
	v_pk_mul_f32 v[16:17], v[16:17], v[92:93]
; #define SBAR() __builtin_amdgcn_sched_barrier(0)
; #define SLOAD(i, k0) do { sv0[i] = *(const bf16x8*)(&Vh[(long)((k0) + sr) * LDK + sc]); sv1[i] = *(const bf16x8*)(&Vh[(long)((k0) + 32 + sr) * LDK + sc]); \
;     sk0[i] = *(const bf16x8*)(&Kh[(long)((k0) + sr) * LDK + sc]); sk1[i] = *(const bf16x8*)(&Kh[(long)((k0) + 32 + sr) * LDK + sc]); } while (0)
; #define RESC(a) do { if (__any((a) < 1.f)) { if (hi == 0) al_l[r32] = (a); asm volatile("s_waitcnt lgkmcnt(0)" ::: "memory"); \
;     _Pragma("unroll") for (int d = 0; d < 4; ++d) _Pragma("unroll") for (int r = 0; r < 16; ++r) o[d][r] *= al_l[crow(r, hi)]; } } while (0)
; __device__ __forceinline__ void attn_dense_body(const bf16_t* __restrict__ Qb, const bf16_t* __restrict__ Kh, const bf16_t* __restrict__ Vh,
;                                                 bf16_t* __restrict__ Ob, int seq, char* lds, int dry) {
;     ...
;         RESC(alB); __syncthreads();
;         { const int t_ = ov; ov = oq; oq = ow; ow = t_; }
;         SBAR(); qkt(pA0, pA1, (bf16_t*)((char*)K_lds + oq), qr, r32, hi);
;         finishSM(pB0, pB1, alB, l_reg, pa0, pa1, pa2, pa3); SBAR();
;         if (j + 3 < NT) SLOAD(0, (j + 3) * KVBLK); SBAR();
.LBB0_273:
	v_mov_b32_e32 v229, v176
	v_fmamk_f32 v176, v69, 0x3e0293ee, v177
	v_fmac_f32_e32 v177, 0x3e0293ee, v70
	s_waitcnt lgkmcnt(0)
	s_barrier
	v_add_u32_e32 v71, s14, v220
	ds_read_b128 v[64:67], v71 offset:49152
	ds_read_b128 v[68:71], v71 offset:57344
	v_add_u32_e32 v137, s14, v222
	ds_read_b128 v[130:133], v137 offset:49152
	ds_read_b128 v[134:137], v137 offset:57344
	v_add_u32_e32 v145, s14, v221
	ds_read_b128 v[138:141], v145 offset:49152
	ds_read_b128 v[142:145], v145 offset:57344
	s_waitcnt lgkmcnt(5)
	v_mfma_f32_32x32x16_bf16 v[80:95], v[64:67], v[126:129], 0
	v_exp_f32_e32 v238, v238
	v_exp_f32_e32 v239, v239
	v_exp_f32_e32 v240, v240
	v_exp_f32_e32 v241, v241
	v_exp_f32_e32 v242, v242
	v_exp_f32_e32 v243, v243
	s_waitcnt lgkmcnt(4)
	v_mfma_f32_32x32x16_bf16 v[64:79], v[68:71], v[126:129], 0
	v_exp_f32_e32 v244, v244
	v_exp_f32_e32 v245, v245
	v_exp_f32_e32 v246, v246
	v_exp_f32_e32 v247, v247
	v_add_f32_e32 v162, 0, v238
	v_exp_f32_e32 v171, v171
	s_waitcnt lgkmcnt(3)
	v_mfma_f32_32x32x16_bf16 v[80:95], v[130:133], v[122:125], v[80:95]
	v_add_f32_e32 v162, v239, v162
	v_exp_f32_e32 v172, v172
	v_add_f32_e32 v162, v240, v162
	v_exp_f32_e32 v173, v173
	v_add_f32_e32 v162, v241, v162
	v_exp_f32_e32 v174, v174
	s_waitcnt lgkmcnt(2)
	v_mfma_f32_32x32x16_bf16 v[64:79], v[134:137], v[122:125], v[64:79]
	v_add_u32_e32 v137, s14, v218
	ds_read_b128 v[130:133], v137 offset:49152
	ds_read_b128 v[134:137], v137 offset:57344
	v_add_f32_e32 v162, v242, v162
	v_exp_f32_e32 v175, v175
	v_add_f32_e32 v162, v243, v162
	v_exp_f32_e32 v176, v176
	v_add_f32_e32 v162, v244, v162
	v_exp_f32_e32 v177, v177
	s_waitcnt lgkmcnt(3)
	v_mfma_f32_32x32x16_bf16 v[80:95], v[138:141], v[118:121], v[80:95]
	v_add_f32_e32 v162, v245, v162
	v_exp_f32_e32 v230, v230
	v_add_f32_e32 v162, v246, v162
	v_exp_f32_e32 v188, v231
	v_add_f32_e32 v162, v247, v162
	v_exp_f32_e32 v186, v232
	s_waitcnt lgkmcnt(2)
	v_mfma_f32_32x32x16_bf16 v[64:79], v[142:145], v[118:121], v[64:79]
	v_add_u32_e32 v145, s14, v215
	ds_read_b128 v[138:141], v145 offset:49152
	ds_read_b128 v[142:145], v145 offset:57344
	v_add_f32_e32 v162, v248, v162
	v_exp_f32_e32 v233, v233
	v_add_f32_e32 v162, v249, v162
	v_exp_f32_e32 v234, v234
	v_add_f32_e32 v162, v250, v162
	s_waitcnt lgkmcnt(3)
	v_mfma_f32_32x32x16_bf16 v[80:95], v[130:133], v[114:117], v[80:95]
	v_exp_f32_e32 v235, v235
	v_add_f32_e32 v162, v251, v162
	v_exp_f32_e32 v236, v236
	v_add_f32_e32 v162, v252, v162
	v_exp_f32_e32 v237, v237
	s_waitcnt lgkmcnt(2)
	v_mfma_f32_32x32x16_bf16 v[64:79], v[134:137], v[114:117], v[64:79]
	v_add_u32_e32 v137, s14, v213
	ds_read_b128 v[130:133], v137 offset:49152
	ds_read_b128 v[134:137], v137 offset:57344
	v_add_f32_e32 v162, v253, v162
	v_exp_f32_e32 v194, v170
	v_add_f32_e32 v162, v171, v162
	v_add_f32_e32 v162, v172, v162
	v_add_f32_e32 v162, v173, v162
	s_waitcnt lgkmcnt(3)
	v_mfma_f32_32x32x16_bf16 v[80:95], v[138:141], v[110:113], v[80:95]
	v_add_f32_e32 v162, v174, v162
	v_add_f32_e32 v162, v175, v162
	v_add_f32_e32 v162, v176, v162
	v_add_f32_e32 v162, v177, v162
	v_add_f32_e32 v162, v230, v162
	s_waitcnt lgkmcnt(2)
	v_mfma_f32_32x32x16_bf16 v[64:79], v[142:145], v[110:113], v[64:79]
	v_add_u32_e32 v145, s14, v223
	ds_read_b128 v[138:141], v145 offset:49152
	ds_read_b128 v[142:145], v145 offset:57344
	v_add_f32_e32 v162, v188, v162
	v_add_f32_e32 v162, v186, v162
	v_add_f32_e32 v162, v233, v162
	v_add_f32_e32 v162, v234, v162
	v_add_f32_e32 v162, v235, v162
	s_waitcnt lgkmcnt(3)
	v_mfma_f32_32x32x16_bf16 v[80:95], v[130:133], v[106:109], v[80:95]
	v_add_f32_e32 v162, v236, v162
	v_add_f32_e32 v162, v237, v162
	v_add_f32_e32 v231, v194, v162
	v_mov_b32_e32 v232, v231
	v_cvt_pk_bf16_f32 v162, v238, v239
	s_waitcnt lgkmcnt(2)
	v_mfma_f32_32x32x16_bf16 v[64:79], v[134:137], v[106:109], v[64:79]
	v_add_u32_e32 v137, s14, v224
	ds_read_b128 v[130:133], v137 offset:49152
	ds_read_b128 v[134:137], v137 offset:57344
	v_cvt_pk_bf16_f32 v163, v240, v241
	v_cvt_pk_bf16_f32 v164, v242, v243
	v_cvt_pk_bf16_f32 v165, v244, v245
	v_cvt_pk_bf16_f32 v166, v246, v247
	v_cvt_pk_bf16_f32 v167, v248, v249
	s_waitcnt lgkmcnt(3)
	v_mfma_f32_32x32x16_bf16 v[80:95], v[138:141], v[102:105], v[80:95]
	v_cvt_pk_bf16_f32 v168, v250, v251
	v_cvt_pk_bf16_f32 v169, v252, v253
	v_cvt_pk_bf16_f32 v170, v171, v172
	v_cvt_pk_bf16_f32 v171, v173, v174
	v_cvt_pk_bf16_f32 v172, v175, v176
	s_waitcnt lgkmcnt(2)
	v_mfma_f32_32x32x16_bf16 v[64:79], v[142:145], v[102:105], v[64:79]
	v_cvt_pk_bf16_f32 v173, v177, v230
	v_cvt_pk_bf16_f32 v174, v188, v186
	v_cvt_pk_bf16_f32 v175, v233, v234
	v_cvt_pk_bf16_f32 v176, v235, v236
	v_cvt_pk_bf16_f32 v177, v237, v194
	s_waitcnt lgkmcnt(1)
	v_mfma_f32_32x32x16_bf16 v[80:95], v[130:133], v[98:101], v[80:95]
	s_nop 1
	v_permlane32_swap_b32_e32 v231, v232
	v_permlane32_swap_b32_e32 v162, v164
	v_permlane32_swap_b32_e32 v163, v165
	v_permlane32_swap_b32_e32 v166, v168
	s_waitcnt lgkmcnt(0)
	v_mfma_f32_32x32x16_bf16 v[64:79], v[134:137], v[98:101], v[64:79]
	v_permlane32_swap_b32_e32 v167, v169
	v_permlane32_swap_b32_e32 v170, v172
	v_permlane32_swap_b32_e32 v171, v173
	v_permlane32_swap_b32_e32 v174, v176
	v_permlane32_swap_b32_e32 v175, v177
	s_add_i32 s38, s38, 2
	s_cmp_ge_u32 s38, s36
	s_cselect_b64 s[10:11], -1, 0
	s_and_b64 vcc, exec, s[10:11]
	s_cbranch_vccnz .LBB0_275
	v_add_co_u32_e32 v130, vcc, 0xfffe8000, v180
	s_nop 1
	v_addc_co_u32_e32 v131, vcc, -1, v181, vcc
	global_load_dwordx4 v[134:137], v[130:131], off
	global_load_dwordx4 v[138:141], v[130:131], off offset:-512
	global_load_dwordx4 v[142:145], v[180:181], off
	s_nop 0
	global_load_dwordx4 v[130:133], v[180:181], off offset:-512

; #define SWRITE(off, i) do { *(bf16x8*)((char*)V_lds + (off) + vst0) = sv0[i];          \
;     *(bf16x8*)((char*)V_lds + (off) + vst1) = sv1[i]; int kc = sc * 2;               \
;     *(bf16x8*)((char*)K_lds + (off) + KSWZ(sr, kc)) = sk0[i];                       \
;     *(bf16x8*)((char*)K_lds + (off) + KSWZ(32 + sr, kc)) = sk1[i]; } while (0)
; #define SWAIT() asm volatile("s_waitcnt vmcnt(4)" ::: "memory")
; #define RESC(a) do { if (__any((a) < 1.f)) { if (hi == 0) al_l[r32] = (a); asm volatile("s_waitcnt lgkmcnt(0)" ::: "memory"); \
;     _Pragma("unroll") for (int d = 0; d < 4; ++d) _Pragma("unroll") for (int r = 0; r < 16; ++r) o[d][r] *= al_l[crow(r, hi)]; } } while (0)
; __device__ __forceinline__ void partialSM(f32x16& p0, f32x16& p1, float& m_reg, float& mn, float& alpha) {
;     constexpr float C = SCALE * 1.4426950408889634f;
;     float pmax = p0[0];
; #pragma unroll
;     for (int r = 1; r < 16; ++r) pmax = fmaxf(pmax, p0[r]);
; #pragma unroll
;     for (int r = 0; r < 16; ++r) pmax = fmaxf(pmax, p1[r]);
;     { auto rr = __builtin_amdgcn_permlane32_swap(__float_as_uint(pmax), __float_as_uint(pmax), false, false);
;       pmax = fmaxf(__uint_as_float(rr[0]), __uint_as_float(rr[1])); }
;     if (__builtin_expect(__all(pmax - m_reg <= THR / SCALE), 1)) { mn = m_reg; alpha = 1.f; }
;     else { mn = fmaxf(m_reg, pmax); alpha = __builtin_amdgcn_exp2f((m_reg - mn) * C); m_reg = mn; }
;     float mnC = -mn * C;
; #pragma unroll
;     for (int r = 0; r < 16; ++r) p0[r] = fmaf(p0[r], C, mnC);
; #pragma unroll
;     for (int r = 0; r < 16; ++r) p1[r] = fmaf(p1[r], C, mnC);
; __device__ __forceinline__ void attn_dense_body(const bf16_t* __restrict__ Qb, const bf16_t* __restrict__ Kh, const bf16_t* __restrict__ Vh,
;                                                 bf16_t* __restrict__ Ob, int seq, char* lds, int dry) {
;     ...
;         pv_d0(o, vb0 + ov, pa0, pa1, pa2, pa3); partialSM(pA0, pA1, m_reg, mnA, alA);
;         SWAIT(); SWRITE(ow, 1);
;         RESC(alA); __syncthreads();
.Lmy_sw_join:
	v_add_u32_e32 v194, s16, v216
	ds_write_b128 v194, v[146:149]
	v_max_f32_e32 v250, v81, v81
	v_max_f32_e32 v251, v80, v80
	v_max_f32_e32 v250, v251, v250
	v_max3_f32 v250, v250, v82, v83
	v_max3_f32 v250, v250, v84, v85
	v_mfma_f32_32x32x16_bf16 v[0:15], v[166:169], v[238:241], v[0:15]
	ds_read_b64_tr_b16 v[238:239], v186 offset:0x1200
	ds_read_b64_tr_b16 v[240:241], v186 offset:0x1a00
	v_add_u32_e32 v194, s16, v217
	ds_write_b128 v194, v[158:161]
	v_max3_f32 v250, v250, v86, v87
	v_max3_f32 v250, v250, v88, v89
	v_max3_f32 v250, v250, v90, v91
	v_max3_f32 v250, v250, v92, v93
	v_max3_f32 v250, v250, v94, v95
	v_mfma_f32_32x32x16_bf16 v[0:15], v[170:173], v[242:245], v[0:15]
	ds_read_b64_tr_b16 v[242:243], v186 offset:0x2200
	ds_read_b64_tr_b16 v[244:245], v186 offset:0x2a00
	v_add_u32_e32 v194, s16, v214
	ds_write_b128 v194, v[150:153] offset:49152
	v_max3_f32 v250, v250, v64, v65
	v_max3_f32 v250, v250, v66, v67
	v_max3_f32 v250, v250, v68, v69
	v_max3_f32 v250, v250, v70, v71
	v_max3_f32 v250, v250, v72, v73
	v_mfma_f32_32x32x16_bf16 v[0:15], v[174:177], v[246:249], v[0:15]
	ds_read_b64_tr_b16 v[246:247], v186 offset:0x3200
	ds_read_b64_tr_b16 v[248:249], v186 offset:0x3a00
	v_add_u32_e32 v194, s16, v219
	ds_write_b128 v194, v[154:157] offset:49152
	v_max3_f32 v250, v250, v74, v75
	v_max3_f32 v250, v250, v76, v77
	v_max3_f32 v250, v250, v78, v79
	v_mov_b32_e32 v251, v250
	s_waitcnt lgkmcnt(0)
	v_mfma_f32_32x32x16_bf16 v[48:63], v[162:165], v[234:237], v[48:63]
	ds_read_b64_tr_b16 v[234:235], v186 offset:0x400
	ds_read_b64_tr_b16 v[236:237], v186 offset:0xc00
	v_permlane32_swap_b32_e32 v250, v251
	v_max_f32_e32 v251, v251, v251
	v_max_f32_e32 v250, v250, v250
	v_max_f32_e32 v250, v250, v251
	v_mfma_f32_32x32x16_bf16 v[48:63], v[166:169], v[238:241], v[48:63]
	ds_read_b64_tr_b16 v[238:239], v186 offset:0x1400
	ds_read_b64_tr_b16 v[240:241], v186 offset:0x1c00
	v_sub_f32_e32 v251, v250, v229
	v_cmp_ge_f32_e32 vcc, s72, v251
	v_max_f32_e32 v251, v229, v229
	v_max_f32_e32 v250, v251, v250
	v_sub_f32_e32 v251, v229, v250
	v_mfma_f32_32x32x16_bf16 v[48:63], v[170:173], v[242:245], v[48:63]
	ds_read_b64_tr_b16 v[242:243], v186 offset:0x2400
	ds_read_b64_tr_b16 v[244:245], v186 offset:0x2c00
	v_mul_f32_e32 v251, 0x3e0293ee, v251
	v_exp_f32_e32 v251, v251
	v_mfma_f32_32x32x16_bf16 v[48:63], v[174:177], v[246:249], v[48:63]
	ds_read_b64_tr_b16 v[246:247], v186 offset:0x3400
	ds_read_b64_tr_b16 v[248:249], v186 offset:0x3c00
	s_cmp_eq_u64 vcc, exec
	s_cselect_b64 s[8:9], -1, 0
	s_nop 0
	v_cndmask_b32_e64 v252, v251, 1.0, s[8:9]
	v_cndmask_b32_e64 v253, v250, v229, s[8:9]
	v_mul_f32_e32 v188, 0xbe0293ee, v253
	s_waitcnt lgkmcnt(0)
	v_mfma_f32_32x32x16_bf16 v[32:47], v[162:165], v[234:237], v[32:47]
	ds_read_b64_tr_b16 v[234:235], v186 offset:0x600
	ds_read_b64_tr_b16 v[236:237], v186 offset:0xe00
	v_fmamk_f32 v230, v85, 0x3e0293ee, v188
	v_fmamk_f32 v229, v83, 0x3e0293ee, v188
	v_fmamk_f32 v160, v64, 0x3e0293ee, v188
	v_fmamk_f32 v161, v65, 0x3e0293ee, v188
	v_fmamk_f32 v158, v66, 0x3e0293ee, v188
	v_mfma_f32_32x32x16_bf16 v[32:47], v[166:169], v[238:241], v[32:47]
	ds_read_b64_tr_b16 v[238:239], v186 offset:0x1600
	ds_read_b64_tr_b16 v[240:241], v186 offset:0x1e00
	v_fmamk_f32 v159, v67, 0x3e0293ee, v188
	v_fmamk_f32 v156, v68, 0x3e0293ee, v188
	v_fmamk_f32 v157, v69, 0x3e0293ee, v188
	v_fmamk_f32 v154, v70, 0x3e0293ee, v188
	v_fmamk_f32 v155, v71, 0x3e0293ee, v188
	v_exp_f32_e32 v230, v230
	v_exp_f32_e32 v229, v229
	v_mfma_f32_32x32x16_bf16 v[32:47], v[170:173], v[242:245], v[32:47]
	ds_read_b64_tr_b16 v[242:243], v186 offset:0x2600
	ds_read_b64_tr_b16 v[244:245], v186 offset:0x2e00
	v_fmamk_f32 v152, v72, 0x3e0293ee, v188
	v_fmamk_f32 v153, v73, 0x3e0293ee, v188
	v_fmamk_f32 v150, v74, 0x3e0293ee, v188
	v_fmamk_f32 v151, v75, 0x3e0293ee, v188
	v_fmamk_f32 v148, v76, 0x3e0293ee, v188
	v_exp_f32_e32 v160, v160
	v_exp_f32_e32 v161, v161
	v_mfma_f32_32x32x16_bf16 v[32:47], v[174:177], v[246:249], v[32:47]
	ds_read_b64_tr_b16 v[246:247], v186 offset:0x3600
	ds_read_b64_tr_b16 v[248:249], v186 offset:0x3e00
	v_fmamk_f32 v149, v77, 0x3e0293ee, v188
	v_fmamk_f32 v146, v78, 0x3e0293ee, v188
	v_fmamk_f32 v147, v79, 0x3e0293ee, v188
	v_exp_f32_e32 v158, v158
	v_exp_f32_e32 v159, v159
	v_exp_f32_e32 v156, v156
	s_waitcnt lgkmcnt(0)
	v_mfma_f32_32x32x16_bf16 v[16:31], v[162:165], v[234:237], v[16:31]
	v_fmamk_f32 v163, v80, 0x3e0293ee, v188
	v_fmamk_f32 v164, v82, 0x3e0293ee, v188
	v_fmamk_f32 v165, v86, 0x3e0293ee, v188
	v_exp_f32_e32 v157, v157
	v_exp_f32_e32 v154, v154
	v_exp_f32_e32 v155, v155
	v_mfma_f32_32x32x16_bf16 v[16:31], v[166:169], v[238:241], v[16:31]
	v_fmamk_f32 v167, v92, 0x3e0293ee, v188
	v_fmamk_f32 v169, v93, 0x3e0293ee, v188
	v_fmamk_f32 v168, v94, 0x3e0293ee, v188
	v_exp_f32_e32 v152, v152
	v_exp_f32_e32 v153, v153
	v_exp_f32_e32 v150, v150
	v_mfma_f32_32x32x16_bf16 v[16:31], v[170:173], v[242:245], v[16:31]
	v_fmamk_f32 v171, v88, 0x3e0293ee, v188
	v_fmamk_f32 v173, v89, 0x3e0293ee, v188
	v_fmamk_f32 v172, v90, 0x3e0293ee, v188
	v_fmamk_f32 v170, v95, 0x3e0293ee, v188
	v_exp_f32_e32 v151, v151
	v_exp_f32_e32 v148, v148
	v_exp_f32_e32 v149, v149
	v_mfma_f32_32x32x16_bf16 v[16:31], v[174:177], v[246:249], v[16:31]
	v_fmamk_f32 v177, v81, 0x3e0293ee, v188
	v_fmamk_f32 v176, v84, 0x3e0293ee, v188
	v_fmamk_f32 v175, v87, 0x3e0293ee, v188
	v_fmamk_f32 v174, v91, 0x3e0293ee, v188
	v_exp_f32_e32 v146, v146
	v_exp_f32_e32 v147, v147
	v_mov_b32_e32 v162, v252
	s_nop 0
	v_cmp_gt_f32_e32 vcc, 1.0, v162
	s_cbranch_vccz .LBB0_279
; #define SBAR() __builtin_amdgcn_sched_barrier(0)
; #define RESC(a) do { if (__any((a) < 1.f)) { if (hi == 0) al_l[r32] = (a); asm volatile("s_waitcnt lgkmcnt(0)" ::: "memory"); \
;     _Pragma("unroll") for (int d = 0; d < 4; ++d) _Pragma("unroll") for (int r = 0; r < 16; ++r) o[d][r] *= al_l[crow(r, hi)]; } } while (0)
; __device__ __forceinline__ void attn_dense_body(const bf16_t* __restrict__ Qb, const bf16_t* __restrict__ Kh, const bf16_t* __restrict__ Vh,
;                                                 bf16_t* __restrict__ Ob, int seq, char* lds, int dry) {
;     ...
;         RESC(alA); __syncthreads();
;         { const int t_ = ov; ov = oq; oq = ow; ow = t_; }
;     }
;     SBAR(); qkt(pB0, pB1, (bf16_t*)((char*)K_lds + oq), qr, r32, hi);
;     finishSM(pA0, pA1, alA, l_reg, pa0, pa1, pa2, pa3); SBAR();
	s_and_saveexec_b64 s[14:15], s[6:7]
	ds_write_b32 v209, v162 offset:128
	s_or_b64 exec, exec, s[14:15]
	s_waitcnt lgkmcnt(0)
	v_add_u32_e32 v250, v179, v96
	ds_read_b128 v[80:83], v250 offset:224
	ds_read_b128 v[84:87], v250 offset:192
	ds_read_b128 v[88:91], v250 offset:160
	ds_read_b128 v[92:95], v250 offset:128
	s_waitcnt lgkmcnt(3)
	v_pk_mul_f32 v[12:13], v[12:13], v[80:81]
	s_waitcnt lgkmcnt(2)
	v_pk_mul_f32 v[8:9], v[8:9], v[84:85]
	s_waitcnt lgkmcnt(1)
	v_pk_mul_f32 v[4:5], v[4:5], v[88:89]
	v_pk_mul_f32 v[14:15], v[14:15], v[82:83]
	v_pk_mul_f32 v[10:11], v[10:11], v[86:87]
	v_pk_mul_f32 v[6:7], v[6:7], v[90:91]
	s_waitcnt lgkmcnt(0)
	v_pk_mul_f32 v[2:3], v[2:3], v[94:95]
	v_pk_mul_f32 v[0:1], v[0:1], v[92:93]
	v_pk_mul_f32 v[60:61], v[60:61], v[80:81]
	v_pk_mul_f32 v[56:57], v[56:57], v[84:85]
	v_pk_mul_f32 v[52:53], v[52:53], v[88:89]
	v_pk_mul_f32 v[62:63], v[62:63], v[82:83]
	v_pk_mul_f32 v[58:59], v[58:59], v[86:87]
	v_pk_mul_f32 v[54:55], v[54:55], v[90:91]
	v_pk_mul_f32 v[50:51], v[50:51], v[94:95]
	v_pk_mul_f32 v[48:49], v[48:49], v[92:93]
	v_pk_mul_f32 v[44:45], v[44:45], v[80:81]
	v_pk_mul_f32 v[40:41], v[40:41], v[84:85]
	v_pk_mul_f32 v[36:37], v[36:37], v[88:89]
	v_pk_mul_f32 v[46:47], v[46:47], v[82:83]
	v_pk_mul_f32 v[42:43], v[42:43], v[86:87]
	v_pk_mul_f32 v[38:39], v[38:39], v[90:91]
	v_pk_mul_f32 v[34:35], v[34:35], v[94:95]
	v_pk_mul_f32 v[32:33], v[32:33], v[92:93]
	v_pk_mul_f32 v[28:29], v[28:29], v[80:81]
	v_pk_mul_f32 v[24:25], v[24:25], v[84:85]
	v_pk_mul_f32 v[20:21], v[20:21], v[88:89]
	v_pk_mul_f32 v[30:31], v[30:31], v[82:83]
	v_pk_mul_f32 v[26:27], v[26:27], v[86:87]
	v_pk_mul_f32 v[22:23], v[22:23], v[90:91]
	v_pk_mul_f32 v[18:19], v[18:19], v[94:95]
	v_pk_mul_f32 v[16:17], v[16:17], v[92:93]
.LBB0_279:
	v_mov_b32_e32 v166, v253
	v_add_f32_e32 v64, v226, v227
	v_fmac_f32_e32 v64, v225, v210
	v_add_f32_e32 v210, v231, v232
	s_mov_b64 s[8:9], 0x60000
	v_fmac_f32_e32 v210, v64, v228
	v_lshl_add_u64 v[180:181], v[180:181], 0, s[8:9]
	s_and_b64 vcc, exec, s[10:11]
	s_waitcnt lgkmcnt(0)
	s_barrier
	s_cbranch_vccnz .LBB0_281
	s_mov_b32 s8, s37
	s_mov_b32 s37, s13
	v_mov_b32_e32 v225, v162
	s_branch .LBB0_269
.LBB0_281:
	v_exp_f32_e32 v163, v163
	v_exp_f32_e32 v177, v177
	v_exp_f32_e32 v164, v164
	v_exp_f32_e32 v176, v176
	v_exp_f32_e32 v165, v165
	v_exp_f32_e32 v175, v175
	v_exp_f32_e32 v171, v171
	v_exp_f32_e32 v173, v173
	v_exp_f32_e32 v172, v172
	v_exp_f32_e32 v174, v174
	v_exp_f32_e32 v167, v167
	v_exp_f32_e32 v169, v169
	v_exp_f32_e32 v168, v168
	v_exp_f32_e32 v170, v170
	v_add_u32_e32 v68, s16, v220
	ds_read_b128 v[64:67], v68 offset:49152
	ds_read_b128 v[68:71], v68 offset:57344
	v_add_u32_e32 v130, s16, v222
	s_waitcnt lgkmcnt(1)
	v_mfma_f32_32x32x16_bf16 v[80:95], v[64:67], v[126:129], 0
	s_waitcnt lgkmcnt(0)
	v_mfma_f32_32x32x16_bf16 v[64:79], v[68:71], v[126:129], 0
	ds_read_b128 v[126:129], v130 offset:49152
	ds_read_b128 v[130:133], v130 offset:57344
	s_waitcnt lgkmcnt(1)
	v_mfma_f32_32x32x16_bf16 v[80:95], v[126:129], v[122:125], v[80:95]
	v_add_u32_e32 v126, s16, v221
	s_waitcnt lgkmcnt(0)
	v_mfma_f32_32x32x16_bf16 v[64:79], v[130:133], v[122:125], v[64:79]
	ds_read_b128 v[122:125], v126 offset:49152
	ds_read_b128 v[126:129], v126 offset:57344
	s_waitcnt lgkmcnt(1)
	v_mfma_f32_32x32x16_bf16 v[80:95], v[122:125], v[118:121], v[80:95]
	v_add_u32_e32 v122, s16, v218
	s_waitcnt lgkmcnt(0)
	v_mfma_f32_32x32x16_bf16 v[64:79], v[126:129], v[118:121], v[64:79]
	ds_read_b128 v[118:121], v122 offset:49152
	ds_read_b128 v[122:125], v122 offset:57344
	s_waitcnt lgkmcnt(1)
	v_mfma_f32_32x32x16_bf16 v[80:95], v[118:121], v[114:117], v[80:95]
	v_add_u32_e32 v118, s16, v215
	s_waitcnt lgkmcnt(0)
	v_mfma_f32_32x32x16_bf16 v[64:79], v[122:125], v[114:117], v[64:79]
	ds_read_b128 v[114:117], v118 offset:49152
	ds_read_b128 v[118:121], v118 offset:57344
	v_mov_b32_e32 v122, v146
	v_mov_b32_e32 v123, v147
	s_waitcnt lgkmcnt(1)
	v_mfma_f32_32x32x16_bf16 v[80:95], v[114:117], v[110:113], v[80:95]
	v_add_u32_e32 v114, s16, v213
	s_waitcnt lgkmcnt(0)
	v_mfma_f32_32x32x16_bf16 v[64:79], v[118:121], v[110:113], v[64:79]
	ds_read_b128 v[110:113], v114 offset:49152
	ds_read_b128 v[114:117], v114 offset:57344
	v_mov_b32_e32 v118, v150
	v_mov_b32_e32 v119, v151
	v_mov_b32_e32 v120, v148
	v_mov_b32_e32 v121, v149
	s_waitcnt lgkmcnt(1)
	v_mfma_f32_32x32x16_bf16 v[80:95], v[110:113], v[106:109], v[80:95]
	v_add_u32_e32 v110, s16, v223
	s_waitcnt lgkmcnt(0)
	v_mfma_f32_32x32x16_bf16 v[64:79], v[114:117], v[106:109], v[64:79]
	ds_read_b128 v[106:109], v110 offset:49152
	ds_read_b128 v[110:113], v110 offset:57344
	v_mov_b32_e32 v114, v154
	v_mov_b32_e32 v115, v155
	v_mov_b32_e32 v116, v152
	v_mov_b32_e32 v117, v153
	s_waitcnt lgkmcnt(1)
	v_mfma_f32_32x32x16_bf16 v[80:95], v[106:109], v[102:105], v[80:95]
	v_add_u32_e32 v106, s16, v224
	s_waitcnt lgkmcnt(0)
	v_mfma_f32_32x32x16_bf16 v[64:79], v[110:113], v[102:105], v[64:79]
	ds_read_b128 v[102:105], v106 offset:49152
	ds_read_b128 v[106:109], v106 offset:57344
	v_mov_b32_e32 v110, v158
	v_mov_b32_e32 v111, v159
	v_mov_b32_e32 v112, v156
	v_mov_b32_e32 v113, v157
	s_waitcnt lgkmcnt(1)
	v_mfma_f32_32x32x16_bf16 v[80:95], v[102:105], v[98:101], v[80:95]
	s_waitcnt lgkmcnt(0)
; #define SBAR() __builtin_amdgcn_sched_barrier(0)
; __device__ __forceinline__ void finishSM(f32x16& p0, f32x16& p1, float alpha, float& l_reg, bf16x8& pa0, bf16x8& pa1, bf16x8& pa2, bf16x8& pa3) {
; #pragma unroll
;     for (int r = 0; r < 16; ++r) p1[r] = __builtin_amdgcn_exp2f(p1[r]);
;     float ps = 0;
; #pragma unroll
;     for (int r = 0; r < 16; ++r) ps += p0[r];
; #pragma unroll
;     for (int r = 0; r < 16; ++r) ps += p1[r];
;     { auto rr = __builtin_amdgcn_permlane32_swap(__float_as_uint(ps), __float_as_uint(ps), false, false);
;       ps = __uint_as_float(rr[0]) + __uint_as_float(rr[1]); }
;     l_reg = l_reg * alpha + ps;
;     ...
;     PK4(p0, 0, pa0); PK4(p0, 8, pa1); PK4(p1, 0, pa2); PK4(p1, 8, pa3);
; __device__ __forceinline__ void attn_dense_body(const bf16_t* __restrict__ Qb, const bf16_t* __restrict__ Kh, const bf16_t* __restrict__ Vh,
;                                                 bf16_t* __restrict__ Ob, int seq, char* lds, int dry) {
;     ...
;     finishSM(pA0, pA1, alA, l_reg, pa0, pa1, pa2, pa3); SBAR();
;     pv_d0(o, vb0 + ov, pa0, pa1, pa2, pa3); partialSM(pB0, pB1, m_reg, mnB, alB);
	v_mfma_f32_32x32x16_bf16 v[64:79], v[106:109], v[98:101], v[64:79]
	v_add_f32_e32 v98, 0, v163
	v_add_f32_e32 v98, v177, v98
	v_add_f32_e32 v98, v164, v98
	v_add_f32_e32 v98, v229, v98
	v_add_f32_e32 v98, v176, v98
	v_add_f32_e32 v98, v230, v98
	v_add_f32_e32 v98, v165, v98
	v_add_f32_e32 v98, v175, v98
	v_add_f32_e32 v98, v171, v98
	v_add_f32_e32 v98, v173, v98
	v_add_f32_e32 v98, v172, v98
	v_add_f32_e32 v98, v174, v98
	v_mov_b32_e32 v108, v160
	v_add_f32_e32 v98, v167, v98
	v_mov_b32_e32 v109, v161
	v_add_f32_e32 v98, v169, v98
	v_add_f32_e32 v98, v168, v98
	v_add_f32_e32 v98, v170, v98
	v_add_f32_e32 v98, v108, v98
	v_add_f32_e32 v98, v109, v98
	v_add_f32_e32 v98, v110, v98
	v_add_f32_e32 v98, v111, v98
	v_add_f32_e32 v98, v112, v98
	v_add_f32_e32 v98, v113, v98
	v_add_f32_e32 v98, v114, v98
	v_add_f32_e32 v98, v115, v98
	v_add_f32_e32 v98, v116, v98
	v_add_f32_e32 v98, v117, v98
	v_add_f32_e32 v98, v118, v98
	v_add_f32_e32 v98, v119, v98
	v_add_f32_e32 v98, v120, v98
	v_add_f32_e32 v98, v121, v98
	v_add_f32_e32 v98, v122, v98
	v_add_f32_e32 v102, v123, v98
	v_mov_b32_e32 v103, v102
	v_cvt_pk_bf16_f32 v98, v163, v177
	v_cvt_pk_bf16_f32 v99, v164, v229
	v_cvt_pk_bf16_f32 v100, v176, v230
	v_cvt_pk_bf16_f32 v101, v165, v175
	s_nop 1
	v_permlane32_swap_b32_e32 v102, v103
	v_permlane32_swap_b32_e32 v98, v100
	v_permlane32_swap_b32_e32 v99, v101
	v_cvt_pk_bf16_f32 v104, v171, v173
	v_cvt_pk_bf16_f32 v105, v172, v174
	v_cvt_pk_bf16_f32 v106, v167, v169
	v_cvt_pk_bf16_f32 v107, v168, v170
	v_cvt_pk_bf16_f32 v108, v108, v109
	v_cvt_pk_bf16_f32 v109, v110, v111
	v_cvt_pk_bf16_f32 v110, v112, v113
	v_cvt_pk_bf16_f32 v111, v114, v115
	v_cvt_pk_bf16_f32 v112, v116, v117
	v_cvt_pk_bf16_f32 v113, v118, v119
	v_cvt_pk_bf16_f32 v114, v120, v121
	v_cvt_pk_bf16_f32 v115, v122, v123
	s_nop 0
	v_permlane32_swap_b32_e32 v104, v106
	v_permlane32_swap_b32_e32 v105, v107
	v_permlane32_swap_b32_e32 v108, v110
	v_permlane32_swap_b32_e32 v109, v111
	v_permlane32_swap_b32_e32 v112, v114
	v_permlane32_swap_b32_e32 v113, v115
	v_add_u32_e32 v132, s12, v212
	ds_read_b64_tr_b16 v[116:117], v132 offset:0
	ds_read_b64_tr_b16 v[118:119], v132 offset:0x800
	ds_read_b64_tr_b16 v[120:121], v132 offset:0x1000
	ds_read_b64_tr_b16 v[122:123], v132 offset:0x1800
	ds_read_b64_tr_b16 v[124:125], v132 offset:0x2000
	ds_read_b64_tr_b16 v[126:127], v132 offset:0x2800
	ds_read_b64_tr_b16 v[128:129], v132 offset:0x3000
	ds_read_b64_tr_b16 v[130:131], v132 offset:0x3800
	s_waitcnt lgkmcnt(0)
	s_nop 0
	v_mfma_f32_32x32x16_bf16 v[0:15], v[98:101], v[116:119], v[0:15]
	ds_read_b64_tr_b16 v[116:117], v132 offset:0x200
	ds_read_b64_tr_b16 v[118:119], v132 offset:0xa00
	v_mfma_f32_32x32x16_bf16 v[0:15], v[104:107], v[120:123], v[0:15]
	ds_read_b64_tr_b16 v[120:121], v132 offset:0x1200
	ds_read_b64_tr_b16 v[122:123], v132 offset:0x1a00
	v_mfma_f32_32x32x16_bf16 v[0:15], v[108:111], v[124:127], v[0:15]
	ds_read_b64_tr_b16 v[124:125], v132 offset:0x2200
	ds_read_b64_tr_b16 v[126:127], v132 offset:0x2a00
	v_mfma_f32_32x32x16_bf16 v[0:15], v[112:115], v[128:131], v[0:15]
	ds_read_b64_tr_b16 v[128:129], v132 offset:0x3200
	ds_read_b64_tr_b16 v[130:131], v132 offset:0x3a00
	s_waitcnt lgkmcnt(0)
	v_mfma_f32_32x32x16_bf16 v[48:63], v[98:101], v[116:119], v[48:63]
	ds_read_b64_tr_b16 v[116:117], v132 offset:0x400
	ds_read_b64_tr_b16 v[118:119], v132 offset:0xc00
	v_mfma_f32_32x32x16_bf16 v[48:63], v[104:107], v[120:123], v[48:63]
	ds_read_b64_tr_b16 v[120:121], v132 offset:0x1400
	ds_read_b64_tr_b16 v[122:123], v132 offset:0x1c00
	v_mfma_f32_32x32x16_bf16 v[48:63], v[108:111], v[124:127], v[48:63]
	ds_read_b64_tr_b16 v[124:125], v132 offset:0x2400
	ds_read_b64_tr_b16 v[126:127], v132 offset:0x2c00
	v_mfma_f32_32x32x16_bf16 v[48:63], v[112:115], v[128:131], v[48:63]
	ds_read_b64_tr_b16 v[128:129], v132 offset:0x3400
	ds_read_b64_tr_b16 v[130:131], v132 offset:0x3c00
	s_waitcnt lgkmcnt(0)
	v_mfma_f32_32x32x16_bf16 v[32:47], v[98:101], v[116:119], v[32:47]
	ds_read_b64_tr_b16 v[116:117], v132 offset:0x600
	ds_read_b64_tr_b16 v[118:119], v132 offset:0xe00
	v_mfma_f32_32x32x16_bf16 v[32:47], v[104:107], v[120:123], v[32:47]
	ds_read_b64_tr_b16 v[120:121], v132 offset:0x1600
	ds_read_b64_tr_b16 v[122:123], v132 offset:0x1e00
	v_mfma_f32_32x32x16_bf16 v[32:47], v[108:111], v[124:127], v[32:47]
	ds_read_b64_tr_b16 v[124:125], v132 offset:0x2600
	ds_read_b64_tr_b16 v[126:127], v132 offset:0x2e00
	v_mfma_f32_32x32x16_bf16 v[32:47], v[112:115], v[128:131], v[32:47]
	ds_read_b64_tr_b16 v[128:129], v132 offset:0x3600
	ds_read_b64_tr_b16 v[130:131], v132 offset:0x3e00
	s_waitcnt lgkmcnt(0)
	v_mfma_f32_32x32x16_bf16 v[16:31], v[98:101], v[116:119], v[16:31]
	v_max_f32_e32 v98, v81, v81
	v_max_f32_e32 v99, v80, v80
	v_max_f32_e32 v98, v99, v98
	v_max3_f32 v98, v98, v82, v83
	v_max3_f32 v98, v98, v84, v85
	v_max3_f32 v98, v98, v86, v87
	v_max3_f32 v98, v98, v88, v89
	v_max3_f32 v98, v98, v90, v91
	v_max3_f32 v98, v98, v92, v93
	v_mfma_f32_32x32x16_bf16 v[16:31], v[104:107], v[120:123], v[16:31]
	v_max3_f32 v98, v98, v94, v95
	v_max3_f32 v98, v98, v64, v65
	v_max3_f32 v98, v98, v66, v67
	v_max3_f32 v98, v98, v68, v69
	v_max3_f32 v98, v98, v70, v71
	v_max3_f32 v98, v98, v72, v73
	v_max3_f32 v98, v98, v74, v75
	v_max3_f32 v98, v98, v76, v77
	v_mfma_f32_32x32x16_bf16 v[16:31], v[108:111], v[124:127], v[16:31]
	v_max3_f32 v98, v98, v78, v79
	v_mov_b32_e32 v99, v98
	s_nop 1
	v_permlane32_swap_b32_e32 v98, v99
	v_max_f32_e32 v99, v99, v99
	v_max_f32_e32 v98, v98, v98
	v_max_f32_e32 v98, v98, v99
	v_sub_f32_e32 v99, v98, v166
	v_cmp_ge_f32_e32 vcc, s72, v99
	v_max_f32_e32 v99, v166, v166
	v_max_f32_e32 v99, v99, v98
	v_mfma_f32_32x32x16_bf16 v[16:31], v[112:115], v[128:131], v[16:31]
	v_sub_f32_e32 v98, v166, v99
	v_mul_f32_e32 v98, 0x3e0293ee, v98
	v_exp_f32_e32 v98, v98
	s_cmp_eq_u64 vcc, exec
	s_cselect_b64 s[8:9], -1, 0
	v_cndmask_b32_e64 v98, v98, 1.0, s[8:9]
	v_cmp_gt_f32_e32 vcc, 1.0, v98
	s_cbranch_vccz .LBB0_285
; #define RESC(a) do { if (__any((a) < 1.f)) { if (hi == 0) al_l[r32] = (a); asm volatile("s_waitcnt lgkmcnt(0)" ::: "memory"); \
;     _Pragma("unroll") for (int d = 0; d < 4; ++d) _Pragma("unroll") for (int r = 0; r < 16; ++r) o[d][r] *= al_l[crow(r, hi)]; } } while (0)
; __device__ __forceinline__ void attn_dense_body(const bf16_t* __restrict__ Qb, const bf16_t* __restrict__ Kh, const bf16_t* __restrict__ Vh,
;                                                 bf16_t* __restrict__ Ob, int seq, char* lds, int dry) {
;     ...
;     pv_d0(o, vb0 + ov, pa0, pa1, pa2, pa3); partialSM(pB0, pB1, m_reg, mnB, alB);
;     RESC(alB);
	s_and_saveexec_b64 s[10:11], s[6:7]
	ds_write_b32 v209, v98 offset:128
	s_or_b64 exec, exec, s[10:11]
	s_waitcnt lgkmcnt(0)
	v_add_u32_e32 v100, v179, v96
	ds_read_b128 v[104:107], v100 offset:224
	ds_read_b128 v[108:111], v100 offset:192
	ds_read_b128 v[112:115], v100 offset:160
	ds_read_b128 v[116:119], v100 offset:128
	s_waitcnt lgkmcnt(3)
	v_pk_mul_f32 v[12:13], v[12:13], v[104:105]
	s_waitcnt lgkmcnt(2)
	v_pk_mul_f32 v[8:9], v[8:9], v[108:109]
	s_waitcnt lgkmcnt(1)
	v_pk_mul_f32 v[4:5], v[4:5], v[112:113]
	v_pk_mul_f32 v[14:15], v[14:15], v[106:107]
	v_pk_mul_f32 v[10:11], v[10:11], v[110:111]
	v_pk_mul_f32 v[6:7], v[6:7], v[114:115]
	s_waitcnt lgkmcnt(0)
	v_pk_mul_f32 v[2:3], v[2:3], v[118:119]
	v_pk_mul_f32 v[0:1], v[0:1], v[116:117]
	v_pk_mul_f32 v[60:61], v[60:61], v[104:105]
	v_pk_mul_f32 v[56:57], v[56:57], v[108:109]
	v_pk_mul_f32 v[52:53], v[52:53], v[112:113]
	v_pk_mul_f32 v[62:63], v[62:63], v[106:107]
	v_pk_mul_f32 v[58:59], v[58:59], v[110:111]
	v_pk_mul_f32 v[54:55], v[54:55], v[114:115]
	v_pk_mul_f32 v[50:51], v[50:51], v[118:119]
	v_pk_mul_f32 v[48:49], v[48:49], v[116:117]
	v_pk_mul_f32 v[44:45], v[44:45], v[104:105]
	v_pk_mul_f32 v[40:41], v[40:41], v[108:109]
	v_pk_mul_f32 v[36:37], v[36:37], v[112:113]
	v_pk_mul_f32 v[46:47], v[46:47], v[106:107]
	v_pk_mul_f32 v[42:43], v[42:43], v[110:111]
	v_pk_mul_f32 v[38:39], v[38:39], v[114:115]
	v_pk_mul_f32 v[34:35], v[34:35], v[118:119]
	v_pk_mul_f32 v[32:33], v[32:33], v[116:117]
	v_pk_mul_f32 v[28:29], v[28:29], v[104:105]
	v_pk_mul_f32 v[24:25], v[24:25], v[108:109]
	v_pk_mul_f32 v[20:21], v[20:21], v[112:113]
	v_pk_mul_f32 v[30:31], v[30:31], v[106:107]
	v_pk_mul_f32 v[26:27], v[26:27], v[110:111]
	v_pk_mul_f32 v[22:23], v[22:23], v[114:115]
	v_pk_mul_f32 v[18:19], v[18:19], v[118:119]
	v_pk_mul_f32 v[16:17], v[16:17], v[116:117]
